# hot loop heads (scan tiles, GEMM K-loops) aligned to 64 B (.p2align 6): code-placement test
# speedup vs baseline: 1.0056x; 1.0056x over previous
; template <int NT>
; __device__ __forceinline__ void gemm_tile(f32x4 (&acc)[4][NT], const bf16_t* A, int lda, const bf16_t* B, int ldb, int K, bf16_t* sm) {
;     ...
;     const bf16_t* gb = B + (size_t)lrow * ldb + lkc * 8;
;     int sbrow[NT];
; #pragma unroll
;     for (int i = 0; i < NT; ++i) { const int g = lrow + 32 * i, W_ = 16 * NT, rem = g % W_; sbrow[i] = (g / W_) * W_ + (rem % NT) * 16 + rem / NT; }
;     u32x4 ra0[4], rb0[NT];
; #pragma unroll
;     for (int i = 0; i < 4; ++i) ra0[i] = *(const u32x4*)(ga + (size_t)(32 * i) * lda);
; #pragma unroll
;     for (int i = 0; i < NT; ++i) rb0[i] = *(const u32x4*)(gb + (size_t)(32 * i) * ldb);
; __device__ __forceinline__ void phase_gemm_resid(const bf16_t* A, int lda, int K, const bf16_t* W, const float* X, float* Y, float scale, bf16_t* sm) {
;     const int G = gridDim.x, NTILES = 136 * 8;
;     const int nfull = (NTILES / G) * G;
;     for (int t = blockIdx.x; t < nfull; t += G) resid_tile<4>(t >> 3, (t & 7) * 128, A, lda, K, W, X, Y, scale, sm);
.LBB0_35:
	v_mov_b32_e32 v118, v192
	v_mov_b32_e32 v36, v192
	s_and_b32 s18, s39, 7
	s_lshl_b32 s18, s18, 3
	s_bfe_u32 s19, s39, 0x30006
	s_or_b32 s18, s18, s19
	s_ashr_i32 s19, s39, 9
	s_lshl_b32 s19, s19, 6
	s_or_b32 s18, s18, s19
	v_ashrrev_i32_e32 v0, 31, v36
	v_ashrrev_i32_e32 v34, 3, v36
	v_lshrrev_b32_e32 v0, 26, v0
	v_add_u32_e32 v0, v34, v0
	v_lshrrev_b32_e32 v1, 6, v0
	v_mul_i32_i24_e32 v1, 64, v1
	v_sub_u32_e32 v1, v34, v1
	v_lshrrev_b16_sdwa v2, v196, sext(v1) dst_sel:DWORD dst_unused:UNUSED_PAD src0_sel:DWORD src1_sel:BYTE_0
	v_and_b32_e32 v2, 3, v2
	v_add_u16_e32 v2, v1, v2
	v_ashrrev_i16_sdwa v3, v197, sext(v2) dst_sel:DWORD dst_unused:UNUSED_PAD src0_sel:DWORD src1_sel:BYTE_0
	v_and_b32_e32 v2, 0xfc, v2
	v_sub_u16_e32 v1, v1, v2
	v_and_b32_e32 v0, 0x7ffffc0, v0
	v_lshlrev_b32_sdwa v1, v198, sext(v1) dst_sel:DWORD dst_unused:UNUSED_PAD src0_sel:DWORD src1_sel:BYTE_0
	v_bfe_i32 v2, v3, 0, 16
	v_add3_u32 v37, v0, v2, v1
	v_add_u32_e32 v0, 32, v34
	v_ashrrev_i32_e32 v1, 31, v0
	v_lshrrev_b32_e32 v1, 26, v1
	v_add_u32_e32 v1, v0, v1
	v_lshrrev_b32_e32 v2, 6, v1
	v_mul_i32_i24_e32 v2, 64, v2
	v_sub_u32_e32 v0, v0, v2
	v_lshrrev_b16_sdwa v2, v196, sext(v0) dst_sel:DWORD dst_unused:UNUSED_PAD src0_sel:DWORD src1_sel:BYTE_0
	v_and_b32_e32 v2, 3, v2
	v_add_u16_e32 v2, v0, v2
	v_ashrrev_i16_sdwa v3, v197, sext(v2) dst_sel:DWORD dst_unused:UNUSED_PAD src0_sel:DWORD src1_sel:BYTE_0
	v_and_b32_e32 v2, 0xfc, v2
	v_sub_u16_e32 v0, v0, v2
	v_and_b32_e32 v1, 0x7ffffc0, v1
	v_lshlrev_b32_sdwa v0, v198, sext(v0) dst_sel:DWORD dst_unused:UNUSED_PAD src0_sel:DWORD src1_sel:BYTE_0
	v_bfe_i32 v2, v3, 0, 16
	v_add3_u32 v38, v1, v2, v0
	v_add_u32_e32 v0, 64, v34
	v_ashrrev_i32_e32 v1, 31, v0
	v_lshrrev_b32_e32 v1, 26, v1
	v_add_u32_e32 v1, v0, v1
	v_lshrrev_b32_e32 v2, 6, v1
	v_mul_i32_i24_e32 v2, 64, v2
	v_sub_u32_e32 v0, v0, v2
	v_lshrrev_b16_sdwa v2, v196, sext(v0) dst_sel:DWORD dst_unused:UNUSED_PAD src0_sel:DWORD src1_sel:BYTE_0
	v_and_b32_e32 v2, 3, v2
	v_add_u16_e32 v2, v0, v2
	v_ashrrev_i16_sdwa v3, v197, sext(v2) dst_sel:DWORD dst_unused:UNUSED_PAD src0_sel:DWORD src1_sel:BYTE_0
	v_and_b32_e32 v2, 0xfc, v2
	v_sub_u16_e32 v0, v0, v2
	v_and_b32_e32 v1, 0x7ffffc0, v1
	v_lshlrev_b32_sdwa v0, v198, sext(v0) dst_sel:DWORD dst_unused:UNUSED_PAD src0_sel:DWORD src1_sel:BYTE_0
	v_bfe_i32 v2, v3, 0, 16
	v_add3_u32 v39, v1, v2, v0
	v_add_u32_e32 v0, 0x60, v34
	v_ashrrev_i32_e32 v1, 31, v0
	v_lshrrev_b32_e32 v1, 26, v1
	v_add_u32_e32 v1, v0, v1
	v_lshrrev_b32_e32 v2, 6, v1
	v_mul_i32_i24_e32 v2, 64, v2
	v_sub_u32_e32 v0, v0, v2
	s_ashr_i32 s19, s18, 31
	v_lshrrev_b16_sdwa v2, v196, sext(v0) dst_sel:DWORD dst_unused:UNUSED_PAD src0_sel:DWORD src1_sel:BYTE_0
	s_lshl_b32 s2, s39, 4
	s_lshl_b64 s[76:77], s[18:19], s97
	v_and_b32_e32 v2, 3, v2
	s_and_b32 s2, s2, 0x380
	s_lshl_b64 s[78:79], s[76:77], 1
	v_add_u16_e32 v2, v0, v2
	s_add_u32 s84, s12, s78
	v_ashrrev_i16_sdwa v3, v197, sext(v2) dst_sel:DWORD dst_unused:UNUSED_PAD src0_sel:DWORD src1_sel:BYTE_0
	v_and_b32_e32 v2, 0xfc, v2
	s_addc_u32 s85, s11, s79
	s_lshl_b32 s19, s2, vcc_lo
	v_sub_u16_e32 v0, v0, v2
	s_lshl_b32 s19, s19, 1
	v_and_b32_e32 v1, 0x7ffffc0, v1
	v_lshlrev_b32_sdwa v0, v198, sext(v0) dst_sel:DWORD dst_unused:UNUSED_PAD src0_sel:DWORD src1_sel:BYTE_0
	v_bfe_i32 v2, v3, 0, 16
	v_ashrrev_i32_e32 v35, 31, v34
	s_add_u32 s76, s13, s19
	v_add3_u32 v40, v1, v2, v0
	v_lshlrev_b64 v[0:1], vcc_lo, v[34:35]
	s_addc_u32 s77, s94, 0
	v_lshlrev_b64 v[100:101], 1, v[0:1]
	v_lshlrev_b32_e32 v2, 4, v36
	v_lshl_add_u64 v[0:1], s[76:77], 0, v[100:101]
	v_and_b32_e32 v12, 0x70, v2
	v_lshl_add_u64 v[18:19], s[84:85], 0, v[100:101]
	v_lshl_add_u64 v[4:5], v[0:1], 0, v[12:13]
	s_mov_b32 s75, s87
	s_mov_b32 s83, s87
	v_lshl_add_u64 v[18:19], v[18:19], 0, v[12:13]
	v_lshl_add_u64 v[0:1], v[4:5], 0, s[86:87]
	v_lshl_add_u64 v[6:7], v[4:5], 0, s[74:75]
	v_lshl_add_u64 v[14:15], v[4:5], 0, s[82:83]
	v_lshl_add_u64 v[20:21], v[18:19], 0, s[86:87]
	v_mov_b32_e32 v250, v4
	v_mov_b32_e32 v251, v5
	s_nop 0
	s_nop 0
	s_nop 0
	s_nop 0
	v_mov_b32_e32 v248, v18
	v_mov_b32_e32 v249, v19
	v_lshl_add_u64 v[20:21], v[18:19], 0, s[74:75]
	v_lshl_add_u64 v[26:27], v[18:19], 0, s[82:83]
	s_nop 0
	v_and_b32_e32 v35, 15, v36
	v_lshrrev_b32_e32 v42, 1, v36
	v_and_or_b32 v35, v42, s3, v35
	v_mul_lo_u32 v42, v35, s89
	v_mul_lo_u32 v43, v34, s89
	v_lshl_add_u64 v[34:35], v[12:13], 0, s[78:79]
	v_and_b32_e32 v41, 48, v36
	v_and_b32_e32 v36, 0x4f, v36
	v_lshl_add_u64 v[102:103], s[42:43], 0, v[34:35]
	v_lshl_add_u64 v[104:105], s[44:45], 0, v[34:35]
	v_lshl_add_u64 v[106:107], s[46:47], 0, v[34:35]
	v_lshl_add_u64 v[108:109], s[40:41], 0, v[34:35]
	v_or_b32_e32 v34, s19, v12
	v_mov_b32_e32 v35, v13
	v_mul_u32_u24_e32 v36, 0xa0, v36
	v_mul_lo_u32 v37, v37, s89
	v_mul_lo_u32 v38, v38, s89
	v_mul_lo_u32 v39, v39, s89
	v_mul_lo_u32 v40, v40, s89
	v_lshl_add_u64 v[110:111], s[48:49], 0, v[34:35]
	v_lshl_add_u64 v[112:113], s[50:51], 0, v[34:35]
	v_lshl_add_u64 v[114:115], s[52:53], 0, v[34:35]
	v_lshl_add_u64 v[116:117], s[54:55], 0, v[34:35]
	v_mov_b32_e32 v34, 0
	v_add_u32_e32 v120, v12, v43
	v_add_u32_e32 v121, v12, v37
	v_add_u32_e32 v122, v12, v38
	v_add_u32_e32 v123, v12, v39
	v_add_u32_e32 v124, v12, v40
	v_add_u32_e32 v119, v41, v42
; __device__ __forceinline__ int tidx() { int t = threadIdx.x; asm volatile("" : "+v"(t)); return t; }
; template <int NT>
; __device__ __forceinline__ void gemm_tile(f32x4 (&acc)[4][NT], const bf16_t* A, int lda, const bf16_t* B, int ldb, int K, bf16_t* sm) {
;     const int tid_ = tidx();
;     bf16_t* sA = sm; bf16_t* sB = sm + 128 * LDT;
;     const int tid = tid_, lane = tid & 63, wid = tid >> 6, wr = wid >> 1, wc = wid & 1;
;     const int fr = lane & 15, fq = lane >> 4;
;     const int lrow = tid >> 3, lkc = tid & 7;
;     const bf16_t* ga = A + (size_t)lrow * lda + lkc * 8;
;     const bf16_t* gb = B + (size_t)lrow * ldb + lkc * 8;
;     int sbrow[NT];
; #pragma unroll
;     for (int i = 0; i < NT; ++i) { const int g = lrow + 32 * i, W_ = 16 * NT, rem = g % W_; sbrow[i] = (g / W_) * W_ + (rem % NT) * 16 + rem / NT; }
;     u32x4 ra0[4], rb0[NT];
; #pragma unroll
;     for (int i = 0; i < 4; ++i) ra0[i] = *(const u32x4*)(ga + (size_t)(32 * i) * lda);
; #pragma unroll
;     for (int i = 0; i < NT; ++i) rb0[i] = *(const u32x4*)(gb + (size_t)(32 * i) * ldb);
;     const int nk = K >> 6;
;     for (int kt = 0; kt < nk; ++kt) {
; template <int NT> __device__ __forceinline__ void zero_acc(f32x4 (&acc)[4][NT]) {
; #pragma unroll
;     for (int mt = 0; mt < 4; ++mt)
; #pragma unroll
;         for (int nt = 0; nt < NT; ++nt) acc[mt][nt] = (f32x4){0.f, 0.f, 0.f, 0.f};
; }
	v_add_u32_e32 v12, v41, v36
	s_mov_b32 s19, vcc_hi
	v_mov_b32_e32 v35, v34
	v_mov_b32_e32 v36, v34
	v_mov_b32_e32 v37, v34
	v_mov_b32_e32 v38, v34
	v_mov_b32_e32 v39, v34
	v_mov_b32_e32 v40, v34
	v_mov_b32_e32 v41, v34
	v_mov_b32_e32 v42, v34
	v_mov_b32_e32 v43, v34
	v_mov_b32_e32 v44, v34
	v_mov_b32_e32 v45, v34
	v_mov_b32_e32 v46, v34
	v_mov_b32_e32 v47, v34
	v_mov_b32_e32 v48, v34
	v_mov_b32_e32 v49, v34
	v_mov_b32_e32 v50, v34
	v_mov_b32_e32 v51, v34
	v_mov_b32_e32 v52, v34
	v_mov_b32_e32 v53, v34
	v_mov_b32_e32 v54, v34
	v_mov_b32_e32 v55, v34
	v_mov_b32_e32 v56, v34
	v_mov_b32_e32 v57, v34
	v_mov_b32_e32 v58, v34
	v_mov_b32_e32 v59, v34
	v_mov_b32_e32 v60, v34
	v_mov_b32_e32 v61, v34
	v_mov_b32_e32 v62, v34
	v_mov_b32_e32 v63, v34
	v_mov_b32_e32 v64, v34
	v_mov_b32_e32 v65, v34
	v_mov_b32_e32 v66, v34
	v_mov_b32_e32 v67, v34
	v_mov_b32_e32 v68, v34
	v_mov_b32_e32 v69, v34
	v_mov_b32_e32 v70, v34
	v_mov_b32_e32 v71, v34
	v_mov_b32_e32 v72, v34
	v_mov_b32_e32 v73, v34
	v_mov_b32_e32 v74, v34
	v_mov_b32_e32 v75, v34
	v_mov_b32_e32 v76, v34
	v_mov_b32_e32 v77, v34
	v_mov_b32_e32 v78, v34
	v_mov_b32_e32 v79, v34
	v_mov_b32_e32 v80, v34
	v_mov_b32_e32 v81, v34
	v_mov_b32_e32 v82, v34
	v_mov_b32_e32 v83, v34
	v_mov_b32_e32 v84, v34
	v_mov_b32_e32 v85, v34
	v_mov_b32_e32 v86, v34
	v_mov_b32_e32 v87, v34
	v_mov_b32_e32 v88, v34
	v_mov_b32_e32 v89, v34
	v_mov_b32_e32 v90, v34
	v_mov_b32_e32 v91, v34
	v_mov_b32_e32 v92, v34
	v_mov_b32_e32 v93, v34
	v_mov_b32_e32 v94, v34
	v_mov_b32_e32 v95, v34
	v_mov_b32_e32 v96, v34
	v_mov_b32_e32 v97, v34
	v_writelane_b32 v234, s90, 0
	v_writelane_b32 v234, s91, 1
	v_writelane_b32 v234, s92, 2
	v_writelane_b32 v234, s93, 3
	v_writelane_b32 v234, s94, 4
	v_writelane_b32 v234, s95, 5
	v_bfe_u32 v160, v192, 3, 3
	v_and_b32_e32 v161, 7, v192
	v_xor_b32_e32 v161, v160, v161
	v_lshlrev_b32_e32 v161, 4, v161
	v_lshrrev_b32_e32 v162, 6, v192
	v_lshl_add_u32 v163, v162, 5, v160
	s_lshl_b32 s95, s96, 1
	v_mul_u32_u24_e32 v163, s95, v163
	v_add_u32_e32 v236, v163, v161
	s_lshl_b32 s95, s96, 4
	s_sub_u32 s95, s95, 0x400
	v_add_u32_e32 v237, s95, v236
	v_add_u32_e32 v238, s95, v237
	v_add_u32_e32 v239, s95, v238
	v_lshrrev_b32_e32 v163, 7, v192
	v_bfe_u32 v162, v192, 6, 1
	v_lshlrev_b32_e32 v163, 6, v163
	v_lshl_add_u32 v163, v160, 2, v163
	v_lshl_add_u32 v163, v162, 1, v163
	s_lshl_b32 s95, s96, 1
	v_mul_u32_u24_e32 v163, s95, v163
	v_add_u32_e32 v240, v163, v161
	s_mul_i32 s95, s96, 64
	s_sub_u32 s95, s95, 0x400
	v_add_u32_e32 v241, s95, v240
	s_mul_i32 s95, s96, 62
	s_add_u32 s95, s95, 0x400
	v_subrev_u32_e32 v242, s95, v241
	s_mul_i32 s95, s96, 64
	s_sub_u32 s95, s95, 0x400
	v_add_u32_e32 v243, s95, v242
	v_and_b32_e32 v160, 15, v192
	v_bfe_u32 v161, v192, 4, 2
	v_and_b32_e32 v162, 7, v160
	v_xor_b32_e32 v161, v161, v162
	v_lshlrev_b32_e32 v161, 4, v161
	v_lshl_add_u32 v161, v160, 7, v161
	v_lshrrev_b32_e32 v162, 7, v192
	v_lshl_add_u32 v244, v162, 13, v161
	v_bfe_u32 v162, v192, 6, 1
	v_lshl_add_u32 v246, v162, 13, v161
	v_add_u32_e32 v246, 0x4000, v246
	v_xor_b32_e32 v245, 64, v244
	v_xor_b32_e32 v247, 64, v246
	v_lshrrev_b32_e32 v160, 6, v192
	s_nop 0
	v_readfirstlane_b32 s94, v160
	v_readfirstlane_b32 s90, v248
	v_readfirstlane_b32 s91, v249
	v_readfirstlane_b32 s92, v250
	v_readfirstlane_b32 s93, v251
	s_lshl_b32 s95, s96, 4
	s_mul_i32 s95, s94, s95
	s_sub_u32 s90, s90, s95
	s_subb_u32 s91, s91, 0
	s_lshl_b32 s95, s96, 4
	s_mul_i32 s95, s94, s95
	s_sub_u32 s92, s92, s95
	s_subb_u32 s93, s93, 0
	s_lshl_b32 s94, s94, 10
	s_waitcnt lgkmcnt(0)
	s_barrier
	s_lshl_b32 s95, s94, 2
	s_add_u32 m0, s95, 0x0
	s_nop 0
	global_load_lds_dwordx4 v236, s[90:91]
	global_load_lds_dwordx4 v237, s[90:91] offset:1024
	global_load_lds_dwordx4 v238, s[90:91] offset:2048
	global_load_lds_dwordx4 v239, s[90:91] offset:3072
	s_mul_i32 s95, s94, 4
	s_add_u32 m0, s95, 0x4000
	s_nop 0
	global_load_lds_dwordx4 v240, s[92:93]
	global_load_lds_dwordx4 v241, s[92:93] offset:1024
	global_load_lds_dwordx4 v242, s[92:93] offset:2048
	global_load_lds_dwordx4 v243, s[92:93] offset:3072
	s_add_u32 s90, s90, 0x80
	s_addc_u32 s91, s91, 0
	s_add_u32 s92, s92, 0x80
	s_addc_u32 s93, s93, 0
	s_waitcnt vmcnt(0)
	s_barrier
	s_lshl_b32 s95, s94, 2
	s_add_u32 m0, s95, 0x8000
	s_nop 0
	global_load_lds_dwordx4 v236, s[90:91]
	global_load_lds_dwordx4 v237, s[90:91] offset:1024
	global_load_lds_dwordx4 v238, s[90:91] offset:2048
	global_load_lds_dwordx4 v239, s[90:91] offset:3072
	s_mul_i32 s95, s94, 4
	s_add_u32 m0, s95, 0xc000
	s_nop 0
	global_load_lds_dwordx4 v240, s[92:93]
	global_load_lds_dwordx4 v241, s[92:93] offset:1024
	global_load_lds_dwordx4 v242, s[92:93] offset:2048
	global_load_lds_dwordx4 v243, s[92:93] offset:3072
	s_add_u32 s90, s90, 0x80
	s_addc_u32 s91, s91, 0
	s_add_u32 s92, s92, 0x80
	s_addc_u32 s93, s93, 0
	ds_read_b128 v[126:129], v244 offset:0
	ds_read_b128 v[130:133], v244 offset:2048
	ds_read_b128 v[134:137], v244 offset:4096
	ds_read_b128 v[138:141], v244 offset:6144
	ds_read_b128 v[142:145], v246 offset:0
	ds_read_b128 v[146:149], v246 offset:2048
	ds_read_b128 v[152:155], v246 offset:4096
	ds_read_b128 v[156:159], v246 offset:6144
	s_lshr_b32 s95, s96, 7
	s_add_i32 s95, s95, -2
	s_cmp_eq_u32 s95, 0
	s_cbranch_scc1 .Lgemm_x36
	.p2align	6

; __device__ __forceinline__ int tidx() { int t = threadIdx.x; asm volatile("" : "+v"(t)); return t; }
; __device__ __forceinline__ void delta_scan_task(KP p, int l, bool samp, int b, int h, int cgp, float* sm) {
;     const int tid_ = tidx();
;     const int tid = tid_, lane = tid & 63, wid = tid >> 6, cc = lane >> 3, ks = lane & 7;
;     const int L = samp ? 8 : 2048, row0 = samp ? TPROMPT + b * 8 : b * 2048;
;     const int e = cgp * 32 + wid * 8 + cc;
;     const bf16_t* Dq = (const bf16_t*)(p->ws + OFF_DQ); const bf16_t* Dk = (const bf16_t*)(p->ws + OFF_DK); const bf16_t* Dv = (const bf16_t*)(p->ws + OFF_DV);
;     const float* Dsc = (const float*)(p->ws + OFF_DSC);
;     float* oraw = (float*)(p->ws + OFF_Y) + (size_t)NTOK * 512;
;     f32x2 S[8];
;     const size_t sbase = samp ? ((size_t)((l * 128 + b) * 4 + h) * 128) * 128 : ((size_t)((l * 8 + b) * 4 + h) * 128) * 128;
; #pragma unroll
;     for (int j = 0; j < 8; ++j) {
;         S[j] = (f32x2){0.f, 0.f};
;         if (samp) {
;             S[j].x = p->in[I_SDELTA][sbase + (size_t)(ks * 16 + 2 * j) * 128 + e];
;             S[j].y = p->in[I_SDELTA][sbase + (size_t)(ks * 16 + 2 * j + 1) * 128 + e];
;         }
;     }
;     const int sstep = tid >> 4, sc = tid & 15;
;     uint4 pk, pq; unsigned pv; float2 psc;
;     const int ntile = (L + 15) >> 4;
;     auto load_tile = [&](int tile) {
;         const int step = tile * 16 + sstep;
;         if (step < L) {
;             const size_t o = (size_t)(row0 + step) * 512 + h * 128 + sc * 8;
;             pk = *(const uint4*)(Dk + o); pq = *(const uint4*)(Dq + o);
;             pv = *(const unsigned*)(Dv + (size_t)(row0 + step) * 512 + h * 128 + cgp * 32 + sc * 2);
;         }
;         if (tid < 16 && tile * 16 + tid < L) psc = *(const float2*)(Dsc + ((size_t)(row0 + tile * 16 + tid) * 4 + h) * 2);
;     };
;     load_tile(0);
;     for (int tile = 0; tile < ntile; ++tile) {
.LBB0_138:
	s_or_b64 exec, exec, s[12:13]
	v_ashrrev_i32_e32 v1, 3, v48
	v_and_b32_e32 v2, -8, v1
	v_readlane_b32 s12, v233, 17
	v_readlane_b32 s2, v233, 19
	v_mov_b32_e32 v9, v13
	v_add_u32_e32 v52, s12, v2
	v_lshlrev_b32_e32 v2, 3, v10
	v_or_b32_e32 v12, s2, v2
	s_lshl_b32 s2, s2, 1
	s_add_u32 s2, s18, s2
	s_addc_u32 s11, s19, 0
	s_lshl_b32 s12, s12, 1
	s_add_u32 s12, s2, s12
	s_addc_u32 s13, s11, 0
	v_bfe_u32 v51, v48, 3, 3
	v_lshlrev_b32_e32 v53, 7, v49
	v_lshl_add_u64 v[24:25], s[12:13], 0, v[8:9]
	v_readlane_b32 s12, v231, 12
	v_or_b32_e32 v54, v53, v2
	s_add_u32 s24, s24, s12
	v_lshlrev_b32_e32 v1, 2, v1
	v_lshlrev_b32_e32 v2, 2, v51
	s_movk_i32 s2, 0xffe0
	s_addc_u32 s25, s25, 0
	v_and_or_b32 v1, v1, s2, v2
	v_readlane_b32 s2, v231, 6
	v_readlane_b32 s13, v231, 13
	s_add_u32 s12, s58, s2
	v_readlane_b32 s2, v231, 7
	v_add_u32_e32 v8, v52, v51
	v_and_b32_e32 v19, 7, v48
	v_lshlrev_b32_e32 v10, 1, v10
	s_addc_u32 s13, s59, s2
	v_ashrrev_i32_e32 v9, 31, v8
	s_waitcnt vmcnt(6)
	v_mov_b32_e32 v30, 0
	v_add_u32_e32 v55, 0x4000, v1
	v_lshlrev_b32_e32 v56, 6, v19
	v_lshl_add_u64 v[26:27], v[8:9], 2, s[12:13]
	s_mov_b32 s2, 0
	v_lshlrev_b32_e32 v57, 2, v10
	v_mov_b32_e32 v31, v30
	v_mov_b32_e32 v44, v30
	v_mov_b32_e32 v45, v30
	v_mov_b32_e32 v38, v30
	v_mov_b32_e32 v39, v30
	v_mov_b32_e32 v36, v30
	v_mov_b32_e32 v37, v30
	v_mov_b32_e32 v34, v30
	v_mov_b32_e32 v35, v30
	v_mov_b32_e32 v32, v30
	v_mov_b32_e32 v33, v30
	v_mov_b32_e32 v40, v30
	v_mov_b32_e32 v41, v30
	v_mov_b32_e32 v42, v30
	v_mov_b32_e32 v43, v30
	s_waitcnt vmcnt(0)
	s_branch .Ldelta_first
	.p2align	6

; __device__ __forceinline__ int tidx() { int t = threadIdx.x; asm volatile("" : "+v"(t)); return t; }
; __device__ __forceinline__ void rwkv_scan_task(KP p, int l, bool samp, int b, int h, int hb, float* sm) {
;     const int tid_ = tidx();
;     const int tid = tid_, lane = tid & 63, wid = tid >> 6, rr = lane >> 3, ks = lane & 7;
;     const int L = samp ? 8 : 2048, row0 = samp ? TPROMPT + b * 8 : b * 2048;
;     const int vrow = hb * 32 + wid * 8 + rr;
;     const float* Rw = (const float*)(p->ws + OFF_RW);
;     const bf16_t* Rkk = (const bf16_t*)(p->ws + OFF_RKK); const bf16_t* Rka = (const bf16_t*)(p->ws + OFF_RKA);
;     const bf16_t* Rkp = (const bf16_t*)(p->ws + OFF_RKP); const bf16_t* Rr = (const bf16_t*)(p->ws + OFF_RR);
;     const bf16_t* Rv = (const bf16_t*)(p->ws + OFF_RV);
;     float* yraw = (float*)(p->ws + OFF_Y);
;     f32x2 S[4];
; #pragma unroll
;     for (int i = 0; i < 4; ++i) S[i] = (f32x2){0.f, 0.f};
;     if (samp) {
;         const float* sp = p->in[I_SRWKV] + ((size_t)((l * 128 + b) * 8 + h) * 64 + vrow) * 64 + ks * 8;
;         const float4 s0 = *(const float4*)sp, s1 = *(const float4*)(sp + 4);
;         S[0] = (f32x2){s0.x, s0.y}; S[1] = (f32x2){s0.z, s0.w}; S[2] = (f32x2){s1.x, s1.y}; S[3] = (f32x2){s1.z, s1.w};
;     }
;     const int sstep = tid >> 4, sc = tid & 15;
;     float4 pw; uint2 pkk, pka, pkp, pr; unsigned pv;
;     const int ntile = (L + 15) >> 4;
;     auto load_tile = [&](int tile) {
;         const int step = tile * 16 + sstep;
;         if (step < L) {
;             const size_t o = (size_t)(row0 + step) * 512 + h * 64 + sc * 4;
;             pw = *(const float4*)(Rw + o);
;             pkk = *(const uint2*)(Rkk + o); pka = *(const uint2*)(Rka + o); pkp = *(const uint2*)(Rkp + o); pr = *(const uint2*)(Rr + o);
;             pv = *(const unsigned*)(Rv + (size_t)(row0 + step) * 512 + h * 64 + hb * 32 + sc * 2);
;         }
;     };
;     load_tile(0);
;     for (int tile = 0; tile < ntile; ++tile) {
.LBB0_156:
	s_or_b64 exec, exec, s[44:45]
	v_readlane_b32 s2, v233, 21
	v_ashrrev_i32_e32 v9, 3, v8
	v_and_b32_e32 v10, -8, v9
	v_or_b32_e32 v24, s2, v4
	s_lshl_b32 s2, s2, 1
	v_readlane_b32 s12, v233, 20
	s_add_u32 s2, s18, s2
	s_addc_u32 s11, s19, 0
	v_add_u32_e32 v32, s12, v10
	s_lshl_b32 s12, s12, 1
	s_add_u32 s12, s2, s12
	v_bfe_u32 v33, v8, 3, 3
	s_addc_u32 s13, s11, 0
	v_readlane_b32 s2, v231, 10
	v_and_b32_e32 v5, 7, v8
	v_lshl_add_u32 v34, v12, 6, v4
	v_lshl_add_u64 v[26:27], v[6:7], 1, s[12:13]
	s_add_u32 s12, s58, s2
	v_readlane_b32 s2, v231, 11
	v_add_u32_e32 v4, v32, v33
	v_lshlrev_b32_e32 v22, 5, v5
	s_addc_u32 s13, s59, s2
	v_ashrrev_i32_e32 v5, 31, v4
	v_lshl_add_u64 v[28:29], v[4:5], 2, s[12:13]
	v_lshlrev_b32_e32 v4, 2, v9
	v_lshlrev_b32_e32 v5, 2, v33
	s_movk_i32 s2, 0xffe0
	v_and_or_b32 v4, v4, s2, v5
	v_add_u32_e32 v36, 0x5000, v4
	v_mov_b32_e32 v4, 0
	v_lshlrev_b32_e32 v35, 7, v12
	v_mov_b32_e32 v25, v13
	s_mov_b32 s11, 0
	v_lshlrev_b32_e32 v37, 2, v6
	v_mov_b32_e32 v5, v4
	v_mov_b32_e32 v6, v4
	v_mov_b32_e32 v7, v4
	v_mov_b32_e32 v8, v4
	v_mov_b32_e32 v9, v4
	v_mov_b32_e32 v10, v4
	v_mov_b32_e32 v11, v4
	s_waitcnt vmcnt(0)
	.p2align	6

; __device__ __forceinline__ int tidx() { int t = threadIdx.x; asm volatile("" : "+v"(t)); return t; }
; template <int NT>
; __device__ __forceinline__ void gemm_tile(f32x4 (&acc)[4][NT], const bf16_t* A, int lda, const bf16_t* B, int ldb, int K, bf16_t* sm) {
;     const int tid_ = tidx();
;     bf16_t* sA = sm; bf16_t* sB = sm + 128 * LDT;
;     const int tid = tid_, lane = tid & 63, wid = tid >> 6, wr = wid >> 1, wc = wid & 1;
;     const int fr = lane & 15, fq = lane >> 4;
;     const int lrow = tid >> 3, lkc = tid & 7;
;     const bf16_t* ga = A + (size_t)lrow * lda + lkc * 8;
;     const bf16_t* gb = B + (size_t)lrow * ldb + lkc * 8;
;     int sbrow[NT];
; #pragma unroll
;     for (int i = 0; i < NT; ++i) { const int g = lrow + 32 * i, W_ = 16 * NT, rem = g % W_; sbrow[i] = (g / W_) * W_ + (rem % NT) * 16 + rem / NT; }
;     u32x4 ra0[4], rb0[NT];
; #pragma unroll
;     for (int i = 0; i < 4; ++i) ra0[i] = *(const u32x4*)(ga + (size_t)(32 * i) * lda);
; __device__ __forceinline__ void gate_tile(int t, const bf16_t* xb, const bf16_t* Wg, bf16_t* G, bf16_t* sm) {
;     const int tid_ = tidx();
;     const int lane = tid_ & 63, wid = tid_ >> 6, wr = wid >> 1, wc = wid & 1, fr = lane & 15, fq = lane >> 4;
;     const int tm = t >> 5, tn = t & 31;
;     f32x4 acc[4][4]; zero_acc<4>(acc);
;     gemm_tile<4>(acc, xb + (size_t)tm * 128 * 1024, 1024, Wg + (size_t)tn * 128 * 1024, 1024, 1024, sm);
.Lq_xcd:
	s_cmpk_lt_u32 s74, 0x220
	s_cbranch_scc0 .LBB0_169
	s_lshr_b32 s14, s2, 2
	s_add_i32 s14, s14, -1
	s_mul_i32 s15, s74, 0x1e2
	s_lshr_b32 s15, s15, 16
	s_mul_i32 s18, s15, 0x88
	s_sub_i32 s18, s74, s18
	s_lshr_b32 s19, s18, 3
	s_and_b32 s18, s18, 7
	s_mul_i32 s14, s14, 17
	s_add_i32 s14, s14, s19
	s_lshl_b32 s15, s15, 3
	s_add_i32 s15, s15, s18
	s_lshl_b32 s14, s14, 5
	s_add_i32 s74, s14, s15
	s_addk_i32 s74, 0x580
	v_mov_b32_e32 v12, v192
	v_mov_b32_e32 v40, v192
	s_add_i32 s2, s74, 0xfffffa80
	v_ashrrev_i32_e32 v0, 31, v40
	s_waitcnt vmcnt(6)
	v_ashrrev_i32_e32 v30, 3, v40
	v_lshrrev_b32_e32 v0, 26, v0
	v_add_u32_e32 v0, v30, v0
	v_lshrrev_b32_e32 v1, 6, v0
	v_mul_i32_i24_e32 v1, 64, v1
	v_sub_u32_e32 v1, v30, v1
	v_lshrrev_b16_sdwa v2, v196, sext(v1) dst_sel:DWORD dst_unused:UNUSED_PAD src0_sel:DWORD src1_sel:BYTE_0
	v_and_b32_e32 v2, 3, v2
	v_add_u16_e32 v2, v1, v2
	v_ashrrev_i16_sdwa v3, v197, sext(v2) dst_sel:DWORD dst_unused:UNUSED_PAD src0_sel:DWORD src1_sel:BYTE_0
	v_and_b32_e32 v2, 0xfc, v2
	v_sub_u16_e32 v1, v1, v2
	v_and_b32_e32 v0, 0x7ffffc0, v0
	v_lshlrev_b32_sdwa v1, v198, sext(v1) dst_sel:DWORD dst_unused:UNUSED_PAD src0_sel:DWORD src1_sel:BYTE_0
	v_bfe_i32 v2, v3, 0, 16
	v_add3_u32 v41, v0, v2, v1
	v_add_u32_e32 v0, 32, v30
	v_ashrrev_i32_e32 v1, 31, v0
	v_lshrrev_b32_e32 v1, 26, v1
	v_add_u32_e32 v1, v0, v1
	v_lshrrev_b32_e32 v2, 6, v1
	v_mul_i32_i24_e32 v2, 64, v2
	v_sub_u32_e32 v0, v0, v2
	v_lshrrev_b16_sdwa v2, v196, sext(v0) dst_sel:DWORD dst_unused:UNUSED_PAD src0_sel:DWORD src1_sel:BYTE_0
	v_and_b32_e32 v2, 3, v2
	v_add_u16_e32 v2, v0, v2
	v_ashrrev_i16_sdwa v3, v197, sext(v2) dst_sel:DWORD dst_unused:UNUSED_PAD src0_sel:DWORD src1_sel:BYTE_0
	v_and_b32_e32 v2, 0xfc, v2
	v_sub_u16_e32 v0, v0, v2
	v_and_b32_e32 v1, 0x7ffffc0, v1
	v_lshlrev_b32_sdwa v0, v198, sext(v0) dst_sel:DWORD dst_unused:UNUSED_PAD src0_sel:DWORD src1_sel:BYTE_0
	v_bfe_i32 v2, v3, 0, 16
	v_add3_u32 v42, v1, v2, v0
	v_add_u32_e32 v0, 64, v30
	v_ashrrev_i32_e32 v1, 31, v0
	v_lshrrev_b32_e32 v1, 26, v1
	v_add_u32_e32 v1, v0, v1
	v_lshrrev_b32_e32 v2, 6, v1
	v_mul_i32_i24_e32 v2, 64, v2
	v_sub_u32_e32 v0, v0, v2
	v_lshrrev_b16_sdwa v2, v196, sext(v0) dst_sel:DWORD dst_unused:UNUSED_PAD src0_sel:DWORD src1_sel:BYTE_0
	v_and_b32_e32 v2, 3, v2
	v_add_u16_e32 v2, v0, v2
	v_ashrrev_i16_sdwa v3, v197, sext(v2) dst_sel:DWORD dst_unused:UNUSED_PAD src0_sel:DWORD src1_sel:BYTE_0
	v_and_b32_e32 v2, 0xfc, v2
	v_sub_u16_e32 v0, v0, v2
	v_and_b32_e32 v1, 0x7ffffc0, v1
	v_lshlrev_b32_sdwa v0, v198, sext(v0) dst_sel:DWORD dst_unused:UNUSED_PAD src0_sel:DWORD src1_sel:BYTE_0
	v_bfe_i32 v2, v3, 0, 16
	v_add3_u32 v43, v1, v2, v0
	v_add_u32_e32 v0, 0x60, v30
	v_ashrrev_i32_e32 v1, 31, v0
	v_lshrrev_b32_e32 v1, 26, v1
	v_add_u32_e32 v1, v0, v1
	v_lshrrev_b32_e32 v2, 6, v1
	v_mul_i32_i24_e32 v2, 64, v2
	v_sub_u32_e32 v0, v0, v2
	s_lshr_b32 s13, s2, 5
	v_lshrrev_b16_sdwa v2, v196, sext(v0) dst_sel:DWORD dst_unused:UNUSED_PAD src0_sel:DWORD src1_sel:BYTE_0
	s_lshl_b32 s86, s13, 17
	v_and_b32_e32 v2, 3, v2
	s_and_b32 s12, s74, 31
	s_lshl_b64 s[14:15], s[86:87], 1
	v_add_u16_e32 v2, v0, v2
	s_add_u32 s18, s80, s14
	v_ashrrev_i16_sdwa v3, v197, sext(v2) dst_sel:DWORD dst_unused:UNUSED_PAD src0_sel:DWORD src1_sel:BYTE_0
	v_and_b32_e32 v2, 0xfc, v2
	s_addc_u32 s19, s81, s15
	s_lshl_b32 s2, s12, 18
	v_sub_u16_e32 v0, v0, v2
	s_add_u32 s22, s11, s2
	v_and_b32_e32 v1, 0x7ffffc0, v1
	v_lshlrev_b32_sdwa v0, v198, sext(v0) dst_sel:DWORD dst_unused:UNUSED_PAD src0_sel:DWORD src1_sel:BYTE_0
	v_bfe_i32 v2, v3, 0, 16
	v_ashrrev_i32_e32 v31, 31, v30
	s_addc_u32 s23, s39, 0
	v_add3_u32 v44, v1, v2, v0
	v_lshlrev_b64 v[32:33], 11, v[30:31]
	v_lshlrev_b32_e32 v2, 4, v40
	v_lshl_add_u64 v[0:1], s[22:23], 0, v[32:33]
	v_and_b32_e32 v38, 0x70, v2
	v_mov_b32_e32 v39, v13
	v_lshl_add_u64 v[8:9], v[0:1], 0, v[38:39]
	v_add_co_u32_e32 v0, vcc, s7, v8
	v_mul_lo_u32 v46, v30, s89
	s_nop 0
	v_addc_co_u32_e32 v1, vcc, 0, v9, vcc
	v_add_co_u32_e32 v10, vcc, s37, v8
	v_mov_b32_e32 v250, v8
	v_mov_b32_e32 v251, v9
	s_nop 0
	v_addc_co_u32_e32 v11, vcc, 0, v9, vcc
	v_add_co_u32_e32 v14, vcc, s73, v8
	v_and_b32_e32 v30, 7, v40
	s_nop 0
	v_addc_co_u32_e32 v15, vcc, 0, v9, vcc
	s_nop 0
	v_lshl_add_u64 v[14:15], s[18:19], 0, v[32:33]
	v_lshl_add_u64 v[26:27], v[14:15], 0, v[38:39]
	v_add_co_u32_e32 v14, vcc, s7, v26
	s_add_u32 s14, s58, s14
	s_nop 0
	v_addc_co_u32_e32 v15, vcc, 0, v27, vcc
	v_add_co_u32_e32 v28, vcc, s37, v26
	v_mov_b32_e32 v248, v26
	v_mov_b32_e32 v249, v27
	s_nop 0
	v_addc_co_u32_e32 v29, vcc, 0, v27, vcc
	v_add_co_u32_e32 v34, vcc, s73, v26
	v_and_b32_e32 v31, 15, v40
	s_nop 0
	v_addc_co_u32_e32 v35, vcc, 0, v27, vcc
	s_nop 0
	v_lshrrev_b32_e32 v39, 1, v40
	v_lshl_or_b32 v32, v30, 4, v32
	s_addc_u32 s15, s59, s15
	v_and_or_b32 v31, v39, s3, v31
	v_and_b32_e32 v39, 0x4f, v40
	v_lshl_add_u64 v[98:99], s[14:15], 0, v[32:33]
	s_add_u32 s14, s58, s2
	v_and_b32_e32 v45, 48, v40
	v_mul_lo_u32 v31, v31, s89
	v_mul_u32_u24_e32 v39, 0xa0, v39
	v_mul_lo_u32 v41, v41, s89
	v_mul_lo_u32 v42, v42, s89
	v_mul_lo_u32 v43, v43, s89
	v_mul_lo_u32 v44, v44, s89
	s_addc_u32 s15, s59, 0
	v_mov_b32_e32 v30, 0
; __device__ __forceinline__ int tidx() { int t = threadIdx.x; asm volatile("" : "+v"(t)); return t; }
; template <int NT>
; __device__ __forceinline__ void gemm_tile(f32x4 (&acc)[4][NT], const bf16_t* A, int lda, const bf16_t* B, int ldb, int K, bf16_t* sm) {
;     const int tid_ = tidx();
;     bf16_t* sA = sm; bf16_t* sB = sm + 128 * LDT;
;     const int tid = tid_, lane = tid & 63, wid = tid >> 6, wr = wid >> 1, wc = wid & 1;
;     const int fr = lane & 15, fq = lane >> 4;
;     const int lrow = tid >> 3, lkc = tid & 7;
;     const bf16_t* ga = A + (size_t)lrow * lda + lkc * 8;
;     const bf16_t* gb = B + (size_t)lrow * ldb + lkc * 8;
;     int sbrow[NT];
; #pragma unroll
;     for (int i = 0; i < NT; ++i) { const int g = lrow + 32 * i, W_ = 16 * NT, rem = g % W_; sbrow[i] = (g / W_) * W_ + (rem % NT) * 16 + rem / NT; }
;     u32x4 ra0[4], rb0[NT];
; #pragma unroll
;     for (int i = 0; i < 4; ++i) ra0[i] = *(const u32x4*)(ga + (size_t)(32 * i) * lda);
; #pragma unroll
;     for (int i = 0; i < NT; ++i) rb0[i] = *(const u32x4*)(gb + (size_t)(32 * i) * ldb);
;     const int nk = K >> 6;
;     for (int kt = 0; kt < nk; ++kt) {
; __device__ __forceinline__ void gate_tile(int t, const bf16_t* xb, const bf16_t* Wg, bf16_t* G, bf16_t* sm) {
;     ...
;     f32x4 acc[4][4]; zero_acc<4>(acc);
;     gemm_tile<4>(acc, xb + (size_t)tm * 128 * 1024, 1024, Wg + (size_t)tn * 128 * 1024, 1024, 1024, sm);
	v_lshl_add_u64 v[100:101], s[14:15], 0, v[32:33]
	s_mov_b64 s[14:15], 0
	v_add_u32_e32 v104, v38, v46
	v_add_u32_e32 v105, v38, v41
	v_add_u32_e32 v106, v38, v42
	v_add_u32_e32 v107, v38, v43
	v_add_u32_e32 v108, v38, v44
	v_add_u32_e32 v103, v45, v31
	v_add_u32_e32 v102, v45, v39
	v_mov_b32_e32 v31, v30
	v_mov_b32_e32 v32, v30
	v_mov_b32_e32 v33, v30
	v_mov_b32_e32 v38, v30
	v_mov_b32_e32 v39, v30
	v_mov_b32_e32 v40, v30
	v_mov_b32_e32 v41, v30
	v_mov_b32_e32 v42, v30
	v_mov_b32_e32 v43, v30
	v_mov_b32_e32 v44, v30
	v_mov_b32_e32 v45, v30
	v_mov_b32_e32 v46, v30
	v_mov_b32_e32 v47, v30
	v_mov_b32_e32 v48, v30
	v_mov_b32_e32 v49, v30
	v_mov_b32_e32 v50, v30
	v_mov_b32_e32 v51, v30
	v_mov_b32_e32 v52, v30
	v_mov_b32_e32 v53, v30
	v_mov_b32_e32 v54, v30
	v_mov_b32_e32 v55, v30
	v_mov_b32_e32 v56, v30
	v_mov_b32_e32 v57, v30
	v_mov_b32_e32 v58, v30
	v_mov_b32_e32 v59, v30
	v_mov_b32_e32 v60, v30
	v_mov_b32_e32 v61, v30
	v_mov_b32_e32 v62, v30
	v_mov_b32_e32 v63, v30
	v_mov_b32_e32 v64, v30
	v_mov_b32_e32 v65, v30
	v_mov_b32_e32 v66, v30
	v_mov_b32_e32 v67, v30
	v_mov_b32_e32 v68, v30
	v_mov_b32_e32 v69, v30
	v_mov_b32_e32 v70, v30
	v_mov_b32_e32 v71, v30
	v_mov_b32_e32 v72, v30
	v_mov_b32_e32 v73, v30
	v_mov_b32_e32 v74, v30
	v_mov_b32_e32 v75, v30
	v_mov_b32_e32 v76, v30
	v_mov_b32_e32 v77, v30
	v_mov_b32_e32 v78, v30
	v_mov_b32_e32 v79, v30
	v_mov_b32_e32 v80, v30
	v_mov_b32_e32 v81, v30
	v_mov_b32_e32 v82, v30
	v_mov_b32_e32 v83, v30
	v_mov_b32_e32 v84, v30
	v_mov_b32_e32 v85, v30
	v_mov_b32_e32 v86, v30
	v_mov_b32_e32 v87, v30
	v_mov_b32_e32 v88, v30
	v_mov_b32_e32 v89, v30
	v_mov_b32_e32 v90, v30
	v_mov_b32_e32 v91, v30
	v_mov_b32_e32 v92, v30
	v_mov_b32_e32 v93, v30
	v_mov_b32_e32 v94, v30
	v_mov_b32_e32 v95, v30
	v_mov_b32_e32 v96, v30
	v_mov_b32_e32 v97, v30
	v_writelane_b32 v234, s90, 0
	v_writelane_b32 v234, s91, 1
	v_writelane_b32 v234, s92, 2
	v_writelane_b32 v234, s93, 3
	v_writelane_b32 v234, s94, 4
	v_writelane_b32 v234, s95, 5
	v_bfe_u32 v160, v192, 3, 3
	v_and_b32_e32 v161, 7, v192
	v_xor_b32_e32 v161, v160, v161
	v_lshlrev_b32_e32 v161, 4, v161
	v_lshrrev_b32_e32 v162, 6, v192
	v_lshl_add_u32 v163, v162, 5, v160
	v_mul_u32_u24_e32 v163, 0x800, v163
	v_add_u32_e32 v236, v163, v161
	v_add_u32_e32 v237, 0x3c00, v236
	v_add_u32_e32 v238, 0x3c00, v237
	v_add_u32_e32 v239, 0x3c00, v238
	v_lshrrev_b32_e32 v163, 7, v192
	v_bfe_u32 v162, v192, 6, 1
	v_lshlrev_b32_e32 v163, 6, v163
	v_lshl_add_u32 v163, v160, 2, v163
	v_lshl_add_u32 v163, v162, 1, v163
	v_mul_u32_u24_e32 v163, 0x800, v163
	v_add_u32_e32 v240, v163, v161
	v_add_u32_e32 v241, 0xfc00, v240
	v_subrev_u32_e32 v242, 0xfc00, v241
	v_add_u32_e32 v243, 0xfc00, v242
	v_and_b32_e32 v160, 15, v192
	v_bfe_u32 v161, v192, 4, 2
	v_and_b32_e32 v162, 7, v160
	v_xor_b32_e32 v161, v161, v162
	v_lshlrev_b32_e32 v161, 4, v161
	v_lshl_add_u32 v161, v160, 7, v161
	v_lshrrev_b32_e32 v162, 7, v192
	v_lshl_add_u32 v244, v162, 13, v161
	v_bfe_u32 v162, v192, 6, 1
	v_lshl_add_u32 v246, v162, 13, v161
	v_add_u32_e32 v246, 0x4000, v246
	v_xor_b32_e32 v245, 64, v244
	v_xor_b32_e32 v247, 64, v246
	v_lshrrev_b32_e32 v160, 6, v192
	s_nop 0
	v_readfirstlane_b32 s94, v160
	v_readfirstlane_b32 s90, v248
	v_readfirstlane_b32 s91, v249
	v_readfirstlane_b32 s92, v250
	v_readfirstlane_b32 s93, v251
	s_mul_i32 s95, s94, 0x4000
	s_sub_u32 s90, s90, s95
	s_subb_u32 s91, s91, 0
	s_mul_i32 s95, s94, 0x4000
	s_sub_u32 s92, s92, s95
	s_subb_u32 s93, s93, 0
	s_lshl_b32 s94, s94, 10
	s_waitcnt lgkmcnt(0)
	s_barrier
	s_lshl_b32 s95, s94, 2
	s_add_u32 m0, s95, 0x0
	s_nop 0
	global_load_lds_dwordx4 v236, s[90:91]
	global_load_lds_dwordx4 v237, s[90:91] offset:1024
	global_load_lds_dwordx4 v238, s[90:91] offset:2048
	global_load_lds_dwordx4 v239, s[90:91] offset:3072
	s_mul_i32 s95, s94, 4
	s_add_u32 m0, s95, 0x4000
	s_nop 0
	global_load_lds_dwordx4 v240, s[92:93]
	global_load_lds_dwordx4 v241, s[92:93] offset:1024
	global_load_lds_dwordx4 v242, s[92:93] offset:2048
	global_load_lds_dwordx4 v243, s[92:93] offset:3072
	s_add_u32 s90, s90, 0x80
	s_addc_u32 s91, s91, 0
	s_add_u32 s92, s92, 0x80
	s_addc_u32 s93, s93, 0
	s_waitcnt vmcnt(0)
	s_barrier
	s_lshl_b32 s95, s94, 2
	s_add_u32 m0, s95, 0x8000
	s_nop 0
	global_load_lds_dwordx4 v236, s[90:91]
	global_load_lds_dwordx4 v237, s[90:91] offset:1024
	global_load_lds_dwordx4 v238, s[90:91] offset:2048
	global_load_lds_dwordx4 v239, s[90:91] offset:3072
	s_mul_i32 s95, s94, 4
	s_add_u32 m0, s95, 0xc000
	s_nop 0
	global_load_lds_dwordx4 v240, s[92:93]
	global_load_lds_dwordx4 v241, s[92:93] offset:1024
	global_load_lds_dwordx4 v242, s[92:93] offset:2048
	global_load_lds_dwordx4 v243, s[92:93] offset:3072
	s_add_u32 s90, s90, 0x80
	s_addc_u32 s91, s91, 0
	s_add_u32 s92, s92, 0x80
	s_addc_u32 s93, s93, 0
	ds_read_b128 v[110:113], v244 offset:0
	ds_read_b128 v[114:117], v244 offset:2048
	ds_read_b128 v[118:121], v244 offset:4096
	ds_read_b128 v[122:125], v244 offset:6144
	ds_read_b128 v[126:129], v246 offset:0
	ds_read_b128 v[130:133], v246 offset:2048
	ds_read_b128 v[134:137], v246 offset:4096
	ds_read_b128 v[138:141], v246 offset:6144
	s_movk_i32 s95, 0x6
	s_cmp_eq_u32 s95, 0
	s_cbranch_scc1 .Lgemm_x178
	.p2align	6

; template <int NT>
; __device__ __forceinline__ void gemm_tile(f32x4 (&acc)[4][NT], const bf16_t* A, int lda, const bf16_t* B, int ldb, int K, bf16_t* sm) {
;     ...
;     const bf16_t* ga = A + (size_t)lrow * lda + lkc * 8;
;     const bf16_t* gb = B + (size_t)lrow * ldb + lkc * 8;
;     int sbrow[NT];
; #pragma unroll
;     for (int i = 0; i < NT; ++i) { const int g = lrow + 32 * i, W_ = 16 * NT, rem = g % W_; sbrow[i] = (g / W_) * W_ + (rem % NT) * 16 + rem / NT; }
;     u32x4 ra0[4], rb0[NT];
; #pragma unroll
;     for (int i = 0; i < 4; ++i) ra0[i] = *(const u32x4*)(ga + (size_t)(32 * i) * lda);
; #pragma unroll
;     for (int i = 0; i < NT; ++i) rb0[i] = *(const u32x4*)(gb + (size_t)(32 * i) * ldb);
; __device__ __forceinline__ void phase_proj(const bf16_t* xb, const bf16_t* W, bf16_t* P, bf16_t* sm) {
;     ...
;     for (int t = blockIdx.x; t < 136 * 37; t += gridDim.x) {
;         const int tm = t / 37, tn = t % 37;
;         f32x4 acc[4][4]; zero_acc<4>(acc);
;         gemm_tile<4>(acc, xb + (size_t)tm * 128 * 1024, 1024, W + (size_t)tn * 128 * 1024, 1024, 1024, sm);
.Lproj_map_done:
	s_mov_b32 s15, 0
	v_ashrrev_i32_e32 v0, 31, v38
	s_waitcnt vmcnt(6)
	v_ashrrev_i32_e32 v30, 3, v38
	v_lshrrev_b32_e32 v0, 26, v0
	v_add_u32_e32 v0, v30, v0
	v_lshrrev_b32_e32 v1, 6, v0
	v_mul_i32_i24_e32 v1, 64, v1
	v_sub_u32_e32 v1, v30, v1
	v_lshrrev_b16_sdwa v2, v196, sext(v1) dst_sel:DWORD dst_unused:UNUSED_PAD src0_sel:DWORD src1_sel:BYTE_0
	v_and_b32_e32 v2, 3, v2
	v_add_u16_e32 v2, v1, v2
	v_ashrrev_i16_sdwa v3, v197, sext(v2) dst_sel:DWORD dst_unused:UNUSED_PAD src0_sel:DWORD src1_sel:BYTE_0
	v_and_b32_e32 v2, 0xfc, v2
	v_sub_u16_e32 v1, v1, v2
	v_and_b32_e32 v0, 0x7ffffc0, v0
	v_lshlrev_b32_sdwa v1, v198, sext(v1) dst_sel:DWORD dst_unused:UNUSED_PAD src0_sel:DWORD src1_sel:BYTE_0
	v_bfe_i32 v2, v3, 0, 16
	v_add3_u32 v39, v0, v2, v1
	v_add_u32_e32 v0, 32, v30
	v_ashrrev_i32_e32 v1, 31, v0
	v_lshrrev_b32_e32 v1, 26, v1
	v_add_u32_e32 v1, v0, v1
	v_lshrrev_b32_e32 v2, 6, v1
	v_mul_i32_i24_e32 v2, 64, v2
	v_sub_u32_e32 v0, v0, v2
	v_lshrrev_b16_sdwa v2, v196, sext(v0) dst_sel:DWORD dst_unused:UNUSED_PAD src0_sel:DWORD src1_sel:BYTE_0
	v_and_b32_e32 v2, 3, v2
	v_add_u16_e32 v2, v0, v2
	v_ashrrev_i16_sdwa v3, v197, sext(v2) dst_sel:DWORD dst_unused:UNUSED_PAD src0_sel:DWORD src1_sel:BYTE_0
	v_and_b32_e32 v2, 0xfc, v2
	v_sub_u16_e32 v0, v0, v2
	v_and_b32_e32 v1, 0x7ffffc0, v1
	v_lshlrev_b32_sdwa v0, v198, sext(v0) dst_sel:DWORD dst_unused:UNUSED_PAD src0_sel:DWORD src1_sel:BYTE_0
	v_bfe_i32 v2, v3, 0, 16
	v_add3_u32 v40, v1, v2, v0
	v_add_u32_e32 v0, 64, v30
	v_ashrrev_i32_e32 v1, 31, v0
	v_lshrrev_b32_e32 v1, 26, v1
	v_add_u32_e32 v1, v0, v1
	v_lshrrev_b32_e32 v2, 6, v1
	v_mul_i32_i24_e32 v2, 64, v2
	v_sub_u32_e32 v0, v0, v2
	v_lshrrev_b16_sdwa v2, v196, sext(v0) dst_sel:DWORD dst_unused:UNUSED_PAD src0_sel:DWORD src1_sel:BYTE_0
	v_and_b32_e32 v2, 3, v2
	v_add_u16_e32 v2, v0, v2
	v_ashrrev_i16_sdwa v3, v197, sext(v2) dst_sel:DWORD dst_unused:UNUSED_PAD src0_sel:DWORD src1_sel:BYTE_0
	v_and_b32_e32 v2, 0xfc, v2
	v_sub_u16_e32 v0, v0, v2
	v_and_b32_e32 v1, 0x7ffffc0, v1
	v_lshlrev_b32_sdwa v0, v198, sext(v0) dst_sel:DWORD dst_unused:UNUSED_PAD src0_sel:DWORD src1_sel:BYTE_0
	v_bfe_i32 v2, v3, 0, 16
	s_waitcnt lgkmcnt(0)
	v_add3_u32 v41, v1, v2, v0
	v_add_u32_e32 v0, 0x60, v30
	v_ashrrev_i32_e32 v1, 31, v0
	v_lshrrev_b32_e32 v1, 26, v1
	v_add_u32_e32 v1, v0, v1
	v_lshrrev_b32_e32 v2, 6, v1
	v_mul_i32_i24_e32 v2, 64, v2
	v_sub_u32_e32 v0, v0, v2
	v_lshrrev_b16_sdwa v2, v196, sext(v0) dst_sel:DWORD dst_unused:UNUSED_PAD src0_sel:DWORD src1_sel:BYTE_0
	s_lshl_b64 s[22:23], s[14:15], 18
	v_and_b32_e32 v2, 3, v2
	s_add_u32 s40, s80, s22
	v_add_u16_e32 v2, v0, v2
	s_addc_u32 s41, s81, s23
	s_ashr_i32 s19, s18, 31
	v_ashrrev_i16_sdwa v3, v197, sext(v2) dst_sel:DWORD dst_unused:UNUSED_PAD src0_sel:DWORD src1_sel:BYTE_0
	v_and_b32_e32 v2, 0xfc, v2
	s_lshl_b64 s[24:25], s[18:19], 18
	v_sub_u16_e32 v0, v0, v2
	s_add_u32 s42, s11, s24
	v_and_b32_e32 v1, 0x7ffffc0, v1
	v_lshlrev_b32_sdwa v0, v198, sext(v0) dst_sel:DWORD dst_unused:UNUSED_PAD src0_sel:DWORD src1_sel:BYTE_0
	v_bfe_i32 v2, v3, 0, 16
	v_ashrrev_i32_e32 v31, 31, v30
	s_addc_u32 s43, s12, s25
	v_add3_u32 v42, v1, v2, v0
	v_lshlrev_b64 v[32:33], 11, v[30:31]
	v_lshlrev_b32_e32 v2, 4, v38
	v_lshl_add_u64 v[0:1], s[42:43], 0, v[32:33]
	v_and_b32_e32 v12, 0x70, v2
	v_lshl_add_u64 v[8:9], v[0:1], 0, v[12:13]
	v_add_co_u32_e32 v0, vcc, s7, v8
	v_and_b32_e32 v31, 15, v38
	s_nop 0
	v_addc_co_u32_e32 v1, vcc, 0, v9, vcc
	v_add_co_u32_e32 v10, vcc, s37, v8
	v_mov_b32_e32 v250, v8
	v_mov_b32_e32 v251, v9
	s_nop 0
	v_addc_co_u32_e32 v11, vcc, 0, v9, vcc
	v_add_co_u32_e32 v14, vcc, s73, v8
	v_lshrrev_b32_e32 v44, 1, v38
	s_nop 0
	v_addc_co_u32_e32 v15, vcc, 0, v9, vcc
	s_nop 0
	v_lshl_add_u64 v[14:15], s[40:41], 0, v[32:33]
	v_lshl_add_u64 v[26:27], v[14:15], 0, v[12:13]
	v_add_co_u32_e32 v14, vcc, s7, v26
	v_and_or_b32 v31, v44, s3, v31
	s_nop 0
	v_addc_co_u32_e32 v15, vcc, 0, v27, vcc
	v_add_co_u32_e32 v28, vcc, s37, v26
	v_mov_b32_e32 v248, v26
	v_mov_b32_e32 v249, v27
	s_nop 0
	v_addc_co_u32_e32 v29, vcc, 0, v27, vcc
	v_add_co_u32_e32 v34, vcc, s73, v26
	v_mul_lo_u32 v44, v31, s89
	s_nop 0
	v_addc_co_u32_e32 v35, vcc, 0, v27, vcc
	s_nop 0
	v_mul_lo_u32 v45, v30, s89
	v_lshl_add_u64 v[30:31], s[22:23], 0, v[32:33]
	v_or_b32_e32 v30, v30, v12
	v_lshl_add_u64 v[98:99], s[58:59], 0, v[30:31]
	v_lshl_add_u64 v[30:31], s[24:25], 0, v[32:33]
	v_and_b32_e32 v43, 48, v38
	v_and_b32_e32 v38, 0x4f, v38
	v_or_b32_e32 v30, v30, v12
	v_mul_u32_u24_e32 v38, 0xa0, v38
	v_mul_lo_u32 v39, v39, s89
	v_mul_lo_u32 v40, v40, s89
	v_mul_lo_u32 v41, v41, s89
	v_mul_lo_u32 v42, v42, s89
	v_lshl_add_u64 v[100:101], s[58:59], 0, v[30:31]
	v_mov_b32_e32 v30, 0
	s_mov_b64 s[22:23], 0
	v_add_u32_e32 v105, v12, v45
	v_add_u32_e32 v106, v12, v39
	v_add_u32_e32 v107, v12, v40
	v_add_u32_e32 v108, v12, v41
	v_add_u32_e32 v109, v12, v42
	v_add_u32_e32 v104, v43, v44
	v_add_u32_e32 v12, v43, v38
; __device__ __forceinline__ int tidx() { int t = threadIdx.x; asm volatile("" : "+v"(t)); return t; }
; template <int NT>
; __device__ __forceinline__ void gemm_tile(f32x4 (&acc)[4][NT], const bf16_t* A, int lda, const bf16_t* B, int ldb, int K, bf16_t* sm) {
;     const int tid_ = tidx();
;     bf16_t* sA = sm; bf16_t* sB = sm + 128 * LDT;
;     const int tid = tid_, lane = tid & 63, wid = tid >> 6, wr = wid >> 1, wc = wid & 1;
;     const int fr = lane & 15, fq = lane >> 4;
;     const int lrow = tid >> 3, lkc = tid & 7;
;     const bf16_t* ga = A + (size_t)lrow * lda + lkc * 8;
;     const bf16_t* gb = B + (size_t)lrow * ldb + lkc * 8;
;     int sbrow[NT];
; #pragma unroll
;     for (int i = 0; i < NT; ++i) { const int g = lrow + 32 * i, W_ = 16 * NT, rem = g % W_; sbrow[i] = (g / W_) * W_ + (rem % NT) * 16 + rem / NT; }
;     u32x4 ra0[4], rb0[NT];
; #pragma unroll
;     for (int i = 0; i < 4; ++i) ra0[i] = *(const u32x4*)(ga + (size_t)(32 * i) * lda);
; #pragma unroll
;     for (int i = 0; i < NT; ++i) rb0[i] = *(const u32x4*)(gb + (size_t)(32 * i) * ldb);
;     const int nk = K >> 6;
;     for (int kt = 0; kt < nk; ++kt) {
; __device__ __forceinline__ void phase_proj(const bf16_t* xb, const bf16_t* W, bf16_t* P, bf16_t* sm) {
;     ...
;         f32x4 acc[4][4]; zero_acc<4>(acc);
;         gemm_tile<4>(acc, xb + (size_t)tm * 128 * 1024, 1024, W + (size_t)tn * 128 * 1024, 1024, 1024, sm);
	v_mov_b32_e32 v31, v30
	v_mov_b32_e32 v32, v30
	v_mov_b32_e32 v33, v30
	v_mov_b32_e32 v38, v30
	v_mov_b32_e32 v39, v30
	v_mov_b32_e32 v40, v30
	v_mov_b32_e32 v41, v30
	v_mov_b32_e32 v42, v30
	v_mov_b32_e32 v43, v30
	v_mov_b32_e32 v44, v30
	v_mov_b32_e32 v45, v30
	v_mov_b32_e32 v46, v30
	v_mov_b32_e32 v47, v30
	v_mov_b32_e32 v48, v30
	v_mov_b32_e32 v49, v30
	v_mov_b32_e32 v50, v30
	v_mov_b32_e32 v51, v30
	v_mov_b32_e32 v52, v30
	v_mov_b32_e32 v53, v30
	v_mov_b32_e32 v54, v30
	v_mov_b32_e32 v55, v30
	v_mov_b32_e32 v56, v30
	v_mov_b32_e32 v57, v30
	v_mov_b32_e32 v58, v30
	v_mov_b32_e32 v59, v30
	v_mov_b32_e32 v60, v30
	v_mov_b32_e32 v61, v30
	v_mov_b32_e32 v62, v30
	v_mov_b32_e32 v63, v30
	v_mov_b32_e32 v64, v30
	v_mov_b32_e32 v65, v30
	v_mov_b32_e32 v66, v30
	v_mov_b32_e32 v67, v30
	v_mov_b32_e32 v68, v30
	v_mov_b32_e32 v69, v30
	v_mov_b32_e32 v70, v30
	v_mov_b32_e32 v71, v30
	v_mov_b32_e32 v72, v30
	v_mov_b32_e32 v73, v30
	v_mov_b32_e32 v74, v30
	v_mov_b32_e32 v75, v30
	v_mov_b32_e32 v76, v30
	v_mov_b32_e32 v77, v30
	v_mov_b32_e32 v78, v30
	v_mov_b32_e32 v79, v30
	v_mov_b32_e32 v80, v30
	v_mov_b32_e32 v81, v30
	v_mov_b32_e32 v82, v30
	v_mov_b32_e32 v83, v30
	v_mov_b32_e32 v84, v30
	v_mov_b32_e32 v85, v30
	v_mov_b32_e32 v86, v30
	v_mov_b32_e32 v87, v30
	v_mov_b32_e32 v88, v30
	v_mov_b32_e32 v89, v30
	v_mov_b32_e32 v90, v30
	v_mov_b32_e32 v91, v30
	v_mov_b32_e32 v92, v30
	v_mov_b32_e32 v93, v30
	v_mov_b32_e32 v94, v30
	v_mov_b32_e32 v95, v30
	v_mov_b32_e32 v96, v30
	v_mov_b32_e32 v97, v30
	v_writelane_b32 v234, s90, 0
	v_writelane_b32 v234, s91, 1
	v_writelane_b32 v234, s92, 2
	v_writelane_b32 v234, s93, 3
	v_writelane_b32 v234, s94, 4
	v_writelane_b32 v234, s95, 5
	v_bfe_u32 v160, v192, 3, 3
	v_and_b32_e32 v161, 7, v192
	v_xor_b32_e32 v161, v160, v161
	v_lshlrev_b32_e32 v161, 4, v161
	v_lshrrev_b32_e32 v162, 6, v192
	v_lshl_add_u32 v163, v162, 5, v160
	v_mul_u32_u24_e32 v163, 0x800, v163
	v_add_u32_e32 v236, v163, v161
	v_add_u32_e32 v237, 0x3c00, v236
	v_add_u32_e32 v238, 0x3c00, v237
	v_add_u32_e32 v239, 0x3c00, v238
	v_lshrrev_b32_e32 v163, 7, v192
	v_bfe_u32 v162, v192, 6, 1
	v_lshlrev_b32_e32 v163, 6, v163
	v_lshl_add_u32 v163, v160, 2, v163
	v_lshl_add_u32 v163, v162, 1, v163
	v_mul_u32_u24_e32 v163, 0x800, v163
	v_add_u32_e32 v240, v163, v161
	v_add_u32_e32 v241, 0xfc00, v240
	v_subrev_u32_e32 v242, 0xfc00, v241
	v_add_u32_e32 v243, 0xfc00, v242
	v_and_b32_e32 v160, 15, v192
	v_bfe_u32 v161, v192, 4, 2
	v_and_b32_e32 v162, 7, v160
	v_xor_b32_e32 v161, v161, v162
	v_lshlrev_b32_e32 v161, 4, v161
	v_lshl_add_u32 v161, v160, 7, v161
	v_lshrrev_b32_e32 v162, 7, v192
	v_lshl_add_u32 v244, v162, 13, v161
	v_bfe_u32 v162, v192, 6, 1
	v_lshl_add_u32 v246, v162, 13, v161
	v_add_u32_e32 v246, 0x4000, v246
	v_xor_b32_e32 v245, 64, v244
	v_xor_b32_e32 v247, 64, v246
	v_lshrrev_b32_e32 v160, 6, v192
	s_nop 0
	v_readfirstlane_b32 s94, v160
	v_readfirstlane_b32 s90, v248
	v_readfirstlane_b32 s91, v249
	v_readfirstlane_b32 s92, v250
	v_readfirstlane_b32 s93, v251
	s_mul_i32 s95, s94, 0x4000
	s_sub_u32 s90, s90, s95
	s_subb_u32 s91, s91, 0
	s_mul_i32 s95, s94, 0x4000
	s_sub_u32 s92, s92, s95
	s_subb_u32 s93, s93, 0
	s_lshl_b32 s94, s94, 10
	s_waitcnt lgkmcnt(0)
	s_barrier
	s_lshl_b32 s95, s94, 2
	s_add_u32 m0, s95, 0x0
	s_nop 0
	global_load_lds_dwordx4 v236, s[90:91]
	global_load_lds_dwordx4 v237, s[90:91] offset:1024
	global_load_lds_dwordx4 v238, s[90:91] offset:2048
	global_load_lds_dwordx4 v239, s[90:91] offset:3072
	s_mul_i32 s95, s94, 4
	s_add_u32 m0, s95, 0x4000
	s_nop 0
	global_load_lds_dwordx4 v240, s[92:93]
	global_load_lds_dwordx4 v241, s[92:93] offset:1024
	global_load_lds_dwordx4 v242, s[92:93] offset:2048
	global_load_lds_dwordx4 v243, s[92:93] offset:3072
	s_add_u32 s90, s90, 0x80
	s_addc_u32 s91, s91, 0
	s_add_u32 s92, s92, 0x80
	s_addc_u32 s93, s93, 0
	s_waitcnt vmcnt(0)
	s_barrier
	s_lshl_b32 s95, s94, 2
	s_add_u32 m0, s95, 0x8000
	s_nop 0
	global_load_lds_dwordx4 v236, s[90:91]
	global_load_lds_dwordx4 v237, s[90:91] offset:1024
	global_load_lds_dwordx4 v238, s[90:91] offset:2048
	global_load_lds_dwordx4 v239, s[90:91] offset:3072
	s_mul_i32 s95, s94, 4
	s_add_u32 m0, s95, 0xc000
	s_nop 0
	global_load_lds_dwordx4 v240, s[92:93]
	global_load_lds_dwordx4 v241, s[92:93] offset:1024
	global_load_lds_dwordx4 v242, s[92:93] offset:2048
	global_load_lds_dwordx4 v243, s[92:93] offset:3072
	s_add_u32 s90, s90, 0x80
	s_addc_u32 s91, s91, 0
	s_add_u32 s92, s92, 0x80
	s_addc_u32 s93, s93, 0
	ds_read_b128 v[110:113], v244 offset:0
	ds_read_b128 v[114:117], v244 offset:2048
	ds_read_b128 v[118:121], v244 offset:4096
	ds_read_b128 v[122:125], v244 offset:6144
	ds_read_b128 v[126:129], v246 offset:0
	ds_read_b128 v[130:133], v246 offset:2048
	ds_read_b128 v[134:137], v246 offset:4096
	ds_read_b128 v[138:141], v246 offset:6144
	s_movk_i32 s95, 0x6
	s_cmp_eq_u32 s95, 0
	s_cbranch_scc1 .Lgemm_x465
	.p2align	6

; __device__ __forceinline__ int tidx() { int t = threadIdx.x; asm volatile("" : "+v"(t)); return t; }
; template <int NT>
; __device__ __forceinline__ void gemm_tile(f32x4 (&acc)[4][NT], const bf16_t* A, int lda, const bf16_t* B, int ldb, int K, bf16_t* sm) {
;     const int tid_ = tidx();
;     bf16_t* sA = sm; bf16_t* sB = sm + 128 * LDT;
;     const int tid = tid_, lane = tid & 63, wid = tid >> 6, wr = wid >> 1, wc = wid & 1;
;     const int fr = lane & 15, fq = lane >> 4;
;     const int lrow = tid >> 3, lkc = tid & 7;
;     const bf16_t* ga = A + (size_t)lrow * lda + lkc * 8;
;     const bf16_t* gb = B + (size_t)lrow * ldb + lkc * 8;
;     int sbrow[NT];
; #pragma unroll
;     for (int i = 0; i < NT; ++i) { const int g = lrow + 32 * i, W_ = 16 * NT, rem = g % W_; sbrow[i] = (g / W_) * W_ + (rem % NT) * 16 + rem / NT; }
;     u32x4 ra0[4], rb0[NT];
; #pragma unroll
;     for (int i = 0; i < 4; ++i) ra0[i] = *(const u32x4*)(ga + (size_t)(32 * i) * lda);
; #pragma unroll
;     for (int i = 0; i < NT; ++i) rb0[i] = *(const u32x4*)(gb + (size_t)(32 * i) * ldb);
;     const int nk = K >> 6;
;     for (int kt = 0; kt < nk; ++kt) {
; __device__ __forceinline__ void phase_merge(const bf16_t* G, const bf16_t* BO, const bf16_t* Wb, bf16_t* M, bf16_t* sm) {
;     ...
;     for (int t = blockIdx.x; t < 136 * 16; t += gridDim.x) {
;         const int tm = t >> 4, tn = t & 15;
;         const int cbase = tn * 64 + wc * 32 + fq * 8;
;         f32x4 accm[4][2]; zero_acc<2>(accm);
; #pragma unroll 1
;         for (int i = 0; i < 4; ++i) {
;             f32x4 accb[4][2]; zero_acc<2>(accb);
;             const int koff = i * 512, kk = i < 3 ? 512 : 256;
;             gemm_tile<2>(accb, BO + (size_t)tm * 128 * 1792 + koff, 1792, Wb + (size_t)tn * 64 * 1792 + koff, 1792, kk, sm);
.LBB0_475:
	v_mov_b32_e32 v28, v192
	s_lshl_b32 s2, s48, 10
	s_add_u32 s40, s44, s2
	v_ashrrev_i32_e32 v0, 31, v28
	v_ashrrev_i32_e32 v26, 3, v28
	v_lshrrev_b32_e32 v0, 27, v0
	s_addc_u32 s41, s45, 0
	v_add_u32_e32 v0, v26, v0
	s_add_u32 s50, s46, s2
	v_lshrrev_b32_e32 v1, 5, v0
	s_addc_u32 s51, s47, 0
	v_mul_i32_i24_e32 v1, 32, v1
	v_sub_u32_e32 v27, v26, v1
	v_and_b32_e32 v29, 0x7ffffe0, v0
	v_mov_b64_e32 v[0:1], s[50:51]
	v_lshlrev_b32_e32 v2, 4, v28
	v_mad_i64_i32 v[0:1], s[50:51], v26, s36, v[0:1]
	v_and_b32_e32 v12, 0x70, v2
	v_lshl_add_u64 v[0:1], v[0:1], 0, v[12:13]
	v_add_co_u32_e32 v2, vcc, s38, v0
	s_mov_b32 s2, 0x38000
	s_nop 0
	v_addc_co_u32_e32 v3, vcc, 0, v1, vcc
	v_mov_b32_e32 v250, v0
	v_mov_b32_e32 v251, v1
	v_mov_b64_e32 v[0:1], s[40:41]
	v_mad_i64_i32 v[0:1], s[40:41], v26, s36, v[0:1]
	s_waitcnt vmcnt(10)
	v_lshl_add_u64 v[18:19], v[0:1], 0, v[12:13]
	v_add_co_u32_e32 v0, vcc, s38, v18
	s_waitcnt vmcnt(8)
	v_lshrrev_b16_e32 v30, 7, v27
	v_addc_co_u32_e32 v1, vcc, 0, v19, vcc
	v_add_co_u32_e32 v20, vcc, s2, v18
	s_mov_b32 s2, 0x54000
	s_nop 0
	v_addc_co_u32_e32 v21, vcc, 0, v19, vcc
	v_add_co_u32_e32 v22, vcc, s2, v18
	v_mov_b32_e32 v248, v18
	v_mov_b32_e32 v249, v19
	s_nop 0
	v_addc_co_u32_e32 v23, vcc, 0, v19, vcc
	s_nop 0
	v_and_b32_e32 v30, 1, v30
	v_add_u16_e32 v30, v27, v30
	v_ashrrev_i16_sdwa v31, v195, sext(v30) dst_sel:DWORD dst_unused:UNUSED_PAD src0_sel:DWORD src1_sel:BYTE_0
	v_and_b32_e32 v30, 0xfe, v30
	v_sub_u16_e32 v27, v27, v30
	v_lshlrev_b32_sdwa v27, v198, sext(v27) dst_sel:DWORD dst_unused:UNUSED_PAD src0_sel:DWORD src1_sel:BYTE_0
	v_bfe_i32 v30, v31, 0, 16
	v_add3_u32 v27, v29, v30, v27
	v_add_u32_e32 v29, 32, v26
	v_ashrrev_i32_e32 v30, 31, v29
	v_lshrrev_b32_e32 v30, 27, v30
	v_add_u32_e32 v30, v29, v30
	v_and_b32_e32 v30, 0xffffffe0, v30
	v_sub_u32_e32 v29, v29, v30
	v_lshrrev_b16_e32 v31, 7, v29
	v_and_b32_e32 v31, 1, v31
	v_add_u16_e32 v31, v29, v31
	v_ashrrev_i16_sdwa v32, v195, sext(v31) dst_sel:DWORD dst_unused:UNUSED_PAD src0_sel:DWORD src1_sel:BYTE_0
	v_and_b32_e32 v31, 0xfe, v31
	v_sub_u16_e32 v29, v29, v31
	v_lshlrev_b32_sdwa v29, v198, sext(v29) dst_sel:DWORD dst_unused:UNUSED_PAD src0_sel:DWORD src1_sel:BYTE_0
	v_bfe_i32 v31, v32, 0, 16
	v_add3_u32 v29, v30, v31, v29
	v_and_b32_e32 v31, 15, v28
	v_lshrrev_b32_e32 v32, 1, v28
	v_and_or_b32 v33, v32, s3, v31
	v_and_b32_e32 v30, 48, v28
	v_and_or_b32 v31, v32, 32, v31
	v_mul_lo_u32 v32, v33, s89
	v_mul_lo_u32 v33, v26, s89
	v_mul_lo_u32 v34, v27, s89
	v_mad_i64_i32 v[26:27], s[40:41], v26, s36, 0
	v_and_b32_e32 v28, 7, v28
	s_cmp_eq_u32 s48, 3
	v_mul_u32_u24_e32 v31, 0xa0, v31
	v_mul_lo_u32 v29, v29, s89
	s_movk_i32 s2, 0x180
	v_lshl_or_b32 v26, v28, 4, v26
	s_cselect_b32 s2, s2, 0x380
	v_lshl_add_u64 v[110:111], s[24:25], 0, v[26:27]
	v_lshl_add_u64 v[112:113], s[22:23], 0, v[26:27]
	s_mov_b64 s[40:41], 0
	v_add_u32_e32 v117, v12, v33
	v_add_u32_e32 v118, v12, v34
	v_add_u32_e32 v119, v12, v29
	v_add_u32_e32 v116, v30, v32
	v_add_u32_e32 v12, v30, v31
	v_mov_b32_e32 v26, 0
	v_mov_b32_e32 v27, v115
	v_mov_b32_e32 v28, v115
	v_mov_b32_e32 v29, v115
	v_mov_b32_e32 v30, 0
	v_mov_b32_e32 v31, v115
	v_mov_b32_e32 v32, v115
	v_mov_b32_e32 v33, v115
	v_mov_b32_e32 v34, 0
	v_mov_b32_e32 v35, v115
	v_mov_b32_e32 v36, v115
	v_mov_b32_e32 v37, v115
	v_mov_b32_e32 v38, 0
	v_mov_b32_e32 v39, v115
	v_mov_b32_e32 v40, v115
	s_waitcnt lgkmcnt(0)
	v_mov_b32_e32 v41, v115
	v_mov_b32_e32 v42, 0
	v_mov_b32_e32 v43, v115
	v_mov_b32_e32 v44, v115
	v_mov_b32_e32 v45, v115
	v_mov_b32_e32 v46, 0
	v_mov_b32_e32 v47, v115
	v_mov_b32_e32 v48, v115
	v_mov_b32_e32 v49, v115
	v_mov_b32_e32 v50, 0
	v_mov_b32_e32 v51, v115
	v_mov_b32_e32 v52, v115
	v_mov_b32_e32 v53, v115
	v_mov_b32_e32 v54, 0
	v_mov_b32_e32 v55, v115
	v_mov_b32_e32 v56, v115
	v_mov_b32_e32 v57, v115
	v_writelane_b32 v234, s90, 0
	v_writelane_b32 v234, s91, 1
	v_writelane_b32 v234, s92, 2
	v_writelane_b32 v234, s93, 3
	v_writelane_b32 v234, s94, 4
	v_writelane_b32 v234, s95, 5
	v_bfe_u32 v160, v192, 3, 3
	v_and_b32_e32 v161, 7, v192
	v_xor_b32_e32 v161, v160, v161
	v_lshlrev_b32_e32 v161, 4, v161
	v_lshrrev_b32_e32 v162, 6, v192
	v_lshl_add_u32 v163, v162, 5, v160
	v_mul_u32_u24_e32 v163, 0xe00, v163
	v_add_u32_e32 v236, v163, v161
	v_add_u32_e32 v237, 0x6c00, v236
	v_add_u32_e32 v238, 0x6c00, v237
	v_add_u32_e32 v239, 0x6c00, v238
	v_lshrrev_b32_e32 v163, 7, v192
	v_bfe_u32 v162, v192, 6, 1
	v_lshlrev_b32_e32 v163, 5, v163
	v_lshl_add_u32 v163, v160, 1, v163
	v_add_u32_e32 v163, v162, v163
	v_mul_u32_u24_e32 v163, 0xe00, v163
	v_add_u32_e32 v240, v163, v161
	v_add_u32_e32 v241, 0xdc00, v240
	v_and_b32_e32 v160, 15, v192
	v_bfe_u32 v161, v192, 4, 2
	v_and_b32_e32 v162, 7, v160
	v_xor_b32_e32 v161, v161, v162
	v_lshlrev_b32_e32 v161, 4, v161
	v_lshl_add_u32 v161, v160, 7, v161
	v_lshrrev_b32_e32 v162, 7, v192
	v_lshl_add_u32 v244, v162, 13, v161
	v_bfe_u32 v162, v192, 6, 1
	v_lshl_add_u32 v246, v162, 12, v161
	v_add_u32_e32 v246, 0x4000, v246
	v_xor_b32_e32 v245, 64, v244
	v_xor_b32_e32 v247, 64, v246
	v_lshrrev_b32_e32 v160, 6, v192
	s_nop 0
	v_readfirstlane_b32 s94, v160
	v_readfirstlane_b32 s90, v248
	v_readfirstlane_b32 s91, v249
	v_readfirstlane_b32 s92, v250
	v_readfirstlane_b32 s93, v251
	s_mul_i32 s95, s94, 0x7000
	s_sub_u32 s90, s90, s95
	s_subb_u32 s91, s91, 0
	s_mul_i32 s95, s94, 0x7000
	s_sub_u32 s92, s92, s95
	s_subb_u32 s93, s93, 0
	s_lshl_b32 s94, s94, 10
	s_waitcnt lgkmcnt(0)
	s_barrier
	s_lshl_b32 s95, s94, 2
	s_add_u32 m0, s95, 0x0
	s_nop 0
	global_load_lds_dwordx4 v236, s[90:91]
	global_load_lds_dwordx4 v237, s[90:91] offset:1024
	global_load_lds_dwordx4 v238, s[90:91] offset:2048
	global_load_lds_dwordx4 v239, s[90:91] offset:3072
	s_mul_i32 s95, s94, 2
	s_add_u32 m0, s95, 0x4000
	s_nop 0
	global_load_lds_dwordx4 v240, s[92:93]
	global_load_lds_dwordx4 v241, s[92:93] offset:1024
	s_add_u32 s90, s90, 0x80
	s_addc_u32 s91, s91, 0
	s_add_u32 s92, s92, 0x80
	s_addc_u32 s93, s93, 0
	s_waitcnt vmcnt(0)
	s_barrier
	s_lshl_b32 s95, s94, 2
	s_add_u32 m0, s95, 0x8000
	s_nop 0
	global_load_lds_dwordx4 v236, s[90:91]
	global_load_lds_dwordx4 v237, s[90:91] offset:1024
	global_load_lds_dwordx4 v238, s[90:91] offset:2048
	global_load_lds_dwordx4 v239, s[90:91] offset:3072
	s_mul_i32 s95, s94, 2
	s_add_u32 m0, s95, 0xc000
	s_nop 0
	global_load_lds_dwordx4 v240, s[92:93]
	global_load_lds_dwordx4 v241, s[92:93] offset:1024
	s_add_u32 s90, s90, 0x80
	s_addc_u32 s91, s91, 0
	s_add_u32 s92, s92, 0x80
	s_addc_u32 s93, s93, 0
	ds_read_b128 v[120:123], v244 offset:0
	ds_read_b128 v[124:127], v244 offset:2048
	ds_read_b128 v[128:131], v244 offset:4096
	ds_read_b128 v[132:135], v244 offset:6144
	ds_read_b128 v[136:139], v246 offset:0
	ds_read_b128 v[140:143], v246 offset:2048
	s_lshr_b32 s95, s2, 8
	s_add_i32 s95, s95, -1
	s_cmp_eq_u32 s95, 0
	s_cbranch_scc1 .Lgemm_x476
	.p2align	6

; __device__ __forceinline__ int tidx() { int t = threadIdx.x; asm volatile("" : "+v"(t)); return t; }
; template <int NT>
; __device__ __forceinline__ void gemm_tile(f32x4 (&acc)[4][NT], const bf16_t* A, int lda, const bf16_t* B, int ldb, int K, bf16_t* sm) {
;     const int tid_ = tidx();
;     bf16_t* sA = sm; bf16_t* sB = sm + 128 * LDT;
;     const int tid = tid_, lane = tid & 63, wid = tid >> 6, wr = wid >> 1, wc = wid & 1;
;     const int fr = lane & 15, fq = lane >> 4;
;     const int lrow = tid >> 3, lkc = tid & 7;
;     const bf16_t* ga = A + (size_t)lrow * lda + lkc * 8;
;     const bf16_t* gb = B + (size_t)lrow * ldb + lkc * 8;
;     int sbrow[NT];
; #pragma unroll
;     for (int i = 0; i < NT; ++i) { const int g = lrow + 32 * i, W_ = 16 * NT, rem = g % W_; sbrow[i] = (g / W_) * W_ + (rem % NT) * 16 + rem / NT; }
;     u32x4 ra0[4], rb0[NT];
; #pragma unroll
;     for (int i = 0; i < 4; ++i) ra0[i] = *(const u32x4*)(ga + (size_t)(32 * i) * lda);
; __device__ __forceinline__ void phase_ffn_in(const bf16_t* xb, const bf16_t* W, bf16_t* H, bf16_t* sm) {
;     const int tid_ = tidx();
;     const int lane = tid_ & 63, wid = tid_ >> 6, wr = wid >> 1, wc = wid & 1, fr = lane & 15, fq = lane >> 4;
;     for (int t = blockIdx.x; t < 136 * 32; t += gridDim.x) {
;         const int tm = t >> 5, tn = t & 31;
;         f32x4 acc[4][4]; zero_acc<4>(acc);
;         gemm_tile<4>(acc, xb + (size_t)tm * 128 * 1024, 1024, W + (size_t)tn * 128 * 1024, 1024, 1024, sm);
.LBB0_1479:
	v_mov_b32_e32 v38, v192
	s_ashr_i32 s18, s11, 5
	v_ashrrev_i32_e32 v0, 31, v38
	v_ashrrev_i32_e32 v30, 3, v38
	v_lshrrev_b32_e32 v0, 26, v0
	v_add_u32_e32 v0, v30, v0
	v_lshrrev_b32_e32 v1, 6, v0
	v_mul_i32_i24_e32 v1, 64, v1
	v_sub_u32_e32 v1, v30, v1
	v_lshrrev_b16_sdwa v2, v196, sext(v1) dst_sel:DWORD dst_unused:UNUSED_PAD src0_sel:DWORD src1_sel:BYTE_0
	v_and_b32_e32 v2, 3, v2
	v_add_u16_e32 v2, v1, v2
	v_ashrrev_i16_sdwa v3, v197, sext(v2) dst_sel:DWORD dst_unused:UNUSED_PAD src0_sel:DWORD src1_sel:BYTE_0
	v_and_b32_e32 v2, 0xfc, v2
	v_sub_u16_e32 v1, v1, v2
	v_and_b32_e32 v0, 0x7ffffc0, v0
	v_lshlrev_b32_sdwa v1, v198, sext(v1) dst_sel:DWORD dst_unused:UNUSED_PAD src0_sel:DWORD src1_sel:BYTE_0
	v_bfe_i32 v2, v3, 0, 16
	v_add3_u32 v39, v0, v2, v1
	v_add_u32_e32 v0, 32, v30
	v_ashrrev_i32_e32 v1, 31, v0
	v_lshrrev_b32_e32 v1, 26, v1
	v_add_u32_e32 v1, v0, v1
	v_lshrrev_b32_e32 v2, 6, v1
	v_mul_i32_i24_e32 v2, 64, v2
	v_sub_u32_e32 v0, v0, v2
	v_lshrrev_b16_sdwa v2, v196, sext(v0) dst_sel:DWORD dst_unused:UNUSED_PAD src0_sel:DWORD src1_sel:BYTE_0
	v_and_b32_e32 v2, 3, v2
	v_add_u16_e32 v2, v0, v2
	v_ashrrev_i16_sdwa v3, v197, sext(v2) dst_sel:DWORD dst_unused:UNUSED_PAD src0_sel:DWORD src1_sel:BYTE_0
	v_and_b32_e32 v2, 0xfc, v2
	v_sub_u16_e32 v0, v0, v2
	v_and_b32_e32 v1, 0x7ffffc0, v1
	v_lshlrev_b32_sdwa v0, v198, sext(v0) dst_sel:DWORD dst_unused:UNUSED_PAD src0_sel:DWORD src1_sel:BYTE_0
	v_bfe_i32 v2, v3, 0, 16
	v_add3_u32 v40, v1, v2, v0
	v_add_u32_e32 v0, 64, v30
	v_ashrrev_i32_e32 v1, 31, v0
	v_lshrrev_b32_e32 v1, 26, v1
	v_add_u32_e32 v1, v0, v1
	v_lshrrev_b32_e32 v2, 6, v1
	v_mul_i32_i24_e32 v2, 64, v2
	v_sub_u32_e32 v0, v0, v2
	v_lshrrev_b16_sdwa v2, v196, sext(v0) dst_sel:DWORD dst_unused:UNUSED_PAD src0_sel:DWORD src1_sel:BYTE_0
	v_and_b32_e32 v2, 3, v2
	v_add_u16_e32 v2, v0, v2
	v_ashrrev_i16_sdwa v3, v197, sext(v2) dst_sel:DWORD dst_unused:UNUSED_PAD src0_sel:DWORD src1_sel:BYTE_0
	v_and_b32_e32 v2, 0xfc, v2
	v_sub_u16_e32 v0, v0, v2
	v_and_b32_e32 v1, 0x7ffffc0, v1
	v_lshlrev_b32_sdwa v0, v198, sext(v0) dst_sel:DWORD dst_unused:UNUSED_PAD src0_sel:DWORD src1_sel:BYTE_0
	v_bfe_i32 v2, v3, 0, 16
	s_waitcnt lgkmcnt(0)
	v_add3_u32 v41, v1, v2, v0
	v_add_u32_e32 v0, 0x60, v30
	v_ashrrev_i32_e32 v1, 31, v0
	v_lshrrev_b32_e32 v1, 26, v1
	v_add_u32_e32 v1, v0, v1
	v_lshrrev_b32_e32 v2, 6, v1
	v_mul_i32_i24_e32 v2, 64, v2
	v_sub_u32_e32 v0, v0, v2
	v_lshrrev_b16_sdwa v2, v196, sext(v0) dst_sel:DWORD dst_unused:UNUSED_PAD src0_sel:DWORD src1_sel:BYTE_0
	s_and_b32 s2, s10, 31
	s_ashr_i32 s19, s18, 31
	v_and_b32_e32 v2, 3, v2
	s_lshl_b32 s86, s2, 18
	s_and_b32 s12, s11, 31
	s_lshl_b64 s[22:23], s[18:19], 18
	v_add_u16_e32 v2, v0, v2
	s_add_u32 s24, s80, s22
	v_ashrrev_i16_sdwa v3, v197, sext(v2) dst_sel:DWORD dst_unused:UNUSED_PAD src0_sel:DWORD src1_sel:BYTE_0
	v_and_b32_e32 v2, 0xfc, v2
	s_addc_u32 s25, s81, s23
	s_lshl_b32 s2, s12, 18
	v_sub_u16_e32 v0, v0, v2
	s_add_u32 s40, s16, s2
	v_and_b32_e32 v1, 0x7ffffc0, v1
	v_lshlrev_b32_sdwa v0, v198, sext(v0) dst_sel:DWORD dst_unused:UNUSED_PAD src0_sel:DWORD src1_sel:BYTE_0
	v_bfe_i32 v2, v3, 0, 16
	v_ashrrev_i32_e32 v31, 31, v30
	s_addc_u32 s41, s17, 0
	v_add3_u32 v42, v1, v2, v0
	v_lshlrev_b64 v[32:33], 11, v[30:31]
	v_lshlrev_b32_e32 v2, 4, v38
	v_lshl_add_u64 v[0:1], s[40:41], 0, v[32:33]
	v_and_b32_e32 v12, 0x70, v2
	v_lshl_add_u64 v[8:9], v[0:1], 0, v[12:13]
	v_add_co_u32_e32 v0, vcc, s7, v8
	v_lshl_add_u64 v[18:19], s[24:25], 0, v[32:33]
	s_nop 0
	v_addc_co_u32_e32 v1, vcc, 0, v9, vcc
	v_add_co_u32_e32 v10, vcc, s37, v8
	v_lshl_add_u64 v[26:27], v[18:19], 0, v[12:13]
	s_nop 0
	v_addc_co_u32_e32 v11, vcc, 0, v9, vcc
	v_add_co_u32_e32 v14, vcc, s73, v8
	v_mov_b32_e32 v250, v8
	v_mov_b32_e32 v251, v9
	s_nop 0
	v_addc_co_u32_e32 v15, vcc, 0, v9, vcc
	v_add_co_u32_e32 v18, vcc, s7, v26
	s_nop 0
	v_addc_co_u32_e32 v19, vcc, 0, v27, vcc
	v_add_co_u32_e32 v28, vcc, s37, v26
	v_mov_b32_e32 v248, v26
	v_mov_b32_e32 v249, v27
	s_nop 0
	v_addc_co_u32_e32 v29, vcc, 0, v27, vcc
	v_add_co_u32_e32 v34, vcc, s73, v26
	v_and_b32_e32 v31, 15, v38
	s_nop 0
	v_addc_co_u32_e32 v35, vcc, 0, v27, vcc
	s_nop 0
	v_lshrrev_b32_e32 v44, 1, v38
	v_and_or_b32 v31, v44, s3, v31
	v_mul_lo_u32 v44, v31, s89
	v_mul_lo_u32 v45, v30, s89
	v_lshl_add_u64 v[30:31], s[22:23], 0, v[32:33]
	v_or_b32_e32 v30, v30, v12
	v_lshl_add_u64 v[98:99], s[58:59], 0, v[30:31]
	v_lshl_add_u64 v[30:31], s[86:87], 0, v[32:33]
	v_and_b32_e32 v43, 48, v38
	v_and_b32_e32 v38, 0x4f, v38
	v_or_b32_e32 v30, v30, v12
	v_mul_u32_u24_e32 v38, 0xa0, v38
	v_mul_lo_u32 v39, v39, s89
	v_mul_lo_u32 v40, v40, s89
	v_mul_lo_u32 v41, v41, s89
	v_mul_lo_u32 v42, v42, s89
	v_lshl_add_u64 v[100:101], s[16:17], 0, v[30:31]
	v_mov_b32_e32 v30, 0
	s_mov_b64 s[22:23], 0
	v_add_u32_e32 v105, v12, v45
	v_add_u32_e32 v106, v12, v39
	v_add_u32_e32 v107, v12, v40
	v_add_u32_e32 v108, v12, v41
	v_add_u32_e32 v109, v12, v42
	v_add_u32_e32 v104, v43, v44
; __device__ __forceinline__ int tidx() { int t = threadIdx.x; asm volatile("" : "+v"(t)); return t; }
; template <int NT>
; __device__ __forceinline__ void gemm_tile(f32x4 (&acc)[4][NT], const bf16_t* A, int lda, const bf16_t* B, int ldb, int K, bf16_t* sm) {
;     const int tid_ = tidx();
;     bf16_t* sA = sm; bf16_t* sB = sm + 128 * LDT;
;     const int tid = tid_, lane = tid & 63, wid = tid >> 6, wr = wid >> 1, wc = wid & 1;
;     const int fr = lane & 15, fq = lane >> 4;
;     const int lrow = tid >> 3, lkc = tid & 7;
;     const bf16_t* ga = A + (size_t)lrow * lda + lkc * 8;
;     const bf16_t* gb = B + (size_t)lrow * ldb + lkc * 8;
;     int sbrow[NT];
; #pragma unroll
;     for (int i = 0; i < NT; ++i) { const int g = lrow + 32 * i, W_ = 16 * NT, rem = g % W_; sbrow[i] = (g / W_) * W_ + (rem % NT) * 16 + rem / NT; }
;     u32x4 ra0[4], rb0[NT];
; #pragma unroll
;     for (int i = 0; i < 4; ++i) ra0[i] = *(const u32x4*)(ga + (size_t)(32 * i) * lda);
; #pragma unroll
;     for (int i = 0; i < NT; ++i) rb0[i] = *(const u32x4*)(gb + (size_t)(32 * i) * ldb);
;     const int nk = K >> 6;
;     for (int kt = 0; kt < nk; ++kt) {
; __device__ __forceinline__ void phase_ffn_in(const bf16_t* xb, const bf16_t* W, bf16_t* H, bf16_t* sm) {
;     ...
;         f32x4 acc[4][4]; zero_acc<4>(acc);
;         gemm_tile<4>(acc, xb + (size_t)tm * 128 * 1024, 1024, W + (size_t)tn * 128 * 1024, 1024, 1024, sm);
	v_add_u32_e32 v12, v43, v38
	v_mov_b32_e32 v31, v30
	v_mov_b32_e32 v32, v30
	v_mov_b32_e32 v33, v30
	v_mov_b32_e32 v38, v30
	v_mov_b32_e32 v39, v30
	v_mov_b32_e32 v40, v30
	v_mov_b32_e32 v41, v30
	v_mov_b32_e32 v42, v30
	v_mov_b32_e32 v43, v30
	v_mov_b32_e32 v44, v30
	v_mov_b32_e32 v45, v30
	v_mov_b32_e32 v46, v30
	v_mov_b32_e32 v47, v30
	v_mov_b32_e32 v48, v30
	v_mov_b32_e32 v49, v30
	v_mov_b32_e32 v50, v30
	v_mov_b32_e32 v51, v30
	v_mov_b32_e32 v52, v30
	v_mov_b32_e32 v53, v30
	v_mov_b32_e32 v54, v30
	v_mov_b32_e32 v55, v30
	v_mov_b32_e32 v56, v30
	v_mov_b32_e32 v57, v30
	v_mov_b32_e32 v58, v30
	v_mov_b32_e32 v59, v30
	v_mov_b32_e32 v60, v30
	v_mov_b32_e32 v61, v30
	v_mov_b32_e32 v62, v30
	v_mov_b32_e32 v63, v30
	v_mov_b32_e32 v64, v30
	v_mov_b32_e32 v65, v30
	v_mov_b32_e32 v66, v30
	v_mov_b32_e32 v67, v30
	v_mov_b32_e32 v68, v30
	v_mov_b32_e32 v69, v30
	v_mov_b32_e32 v70, v30
	v_mov_b32_e32 v71, v30
	v_mov_b32_e32 v72, v30
	v_mov_b32_e32 v73, v30
	v_mov_b32_e32 v74, v30
	v_mov_b32_e32 v75, v30
	v_mov_b32_e32 v76, v30
	v_mov_b32_e32 v77, v30
	v_mov_b32_e32 v78, v30
	v_mov_b32_e32 v79, v30
	v_mov_b32_e32 v80, v30
	v_mov_b32_e32 v81, v30
	v_mov_b32_e32 v82, v30
	v_mov_b32_e32 v83, v30
	v_mov_b32_e32 v84, v30
	v_mov_b32_e32 v85, v30
	v_mov_b32_e32 v86, v30
	v_mov_b32_e32 v87, v30
	v_mov_b32_e32 v88, v30
	v_mov_b32_e32 v89, v30
	v_mov_b32_e32 v90, v30
	v_mov_b32_e32 v91, v30
	v_mov_b32_e32 v92, v30
	v_mov_b32_e32 v93, v30
	v_mov_b32_e32 v94, v30
	v_mov_b32_e32 v95, v30
	v_mov_b32_e32 v96, v30
	v_mov_b32_e32 v97, v30
	v_writelane_b32 v234, s90, 0
	v_writelane_b32 v234, s91, 1
	v_writelane_b32 v234, s92, 2
	v_writelane_b32 v234, s93, 3
	v_writelane_b32 v234, s94, 4
	v_writelane_b32 v234, s95, 5
	v_bfe_u32 v160, v192, 3, 3
	v_and_b32_e32 v161, 7, v192
	v_xor_b32_e32 v161, v160, v161
	v_lshlrev_b32_e32 v161, 4, v161
	v_lshrrev_b32_e32 v162, 6, v192
	v_lshl_add_u32 v163, v162, 5, v160
	v_mul_u32_u24_e32 v163, 0x800, v163
	v_add_u32_e32 v236, v163, v161
	v_add_u32_e32 v237, 0x3c00, v236
	v_add_u32_e32 v238, 0x3c00, v237
	v_add_u32_e32 v239, 0x3c00, v238
	v_lshrrev_b32_e32 v163, 7, v192
	v_bfe_u32 v162, v192, 6, 1
	v_lshlrev_b32_e32 v163, 6, v163
	v_lshl_add_u32 v163, v160, 2, v163
	v_lshl_add_u32 v163, v162, 1, v163
	v_mul_u32_u24_e32 v163, 0x800, v163
	v_add_u32_e32 v240, v163, v161
	v_add_u32_e32 v241, 0xfc00, v240
	v_subrev_u32_e32 v242, 0xfc00, v241
	v_add_u32_e32 v243, 0xfc00, v242
	v_and_b32_e32 v160, 15, v192
	v_bfe_u32 v161, v192, 4, 2
	v_and_b32_e32 v162, 7, v160
	v_xor_b32_e32 v161, v161, v162
	v_lshlrev_b32_e32 v161, 4, v161
	v_lshl_add_u32 v161, v160, 7, v161
	v_lshrrev_b32_e32 v162, 7, v192
	v_lshl_add_u32 v244, v162, 13, v161
	v_bfe_u32 v162, v192, 6, 1
	v_lshl_add_u32 v246, v162, 13, v161
	v_add_u32_e32 v246, 0x4000, v246
	v_xor_b32_e32 v245, 64, v244
	v_xor_b32_e32 v247, 64, v246
	v_lshrrev_b32_e32 v160, 6, v192
	s_nop 0
	v_readfirstlane_b32 s94, v160
	v_readfirstlane_b32 s90, v248
	v_readfirstlane_b32 s91, v249
	v_readfirstlane_b32 s92, v250
	v_readfirstlane_b32 s93, v251
	s_mul_i32 s95, s94, 0x4000
	s_sub_u32 s90, s90, s95
	s_subb_u32 s91, s91, 0
	s_mul_i32 s95, s94, 0x4000
	s_sub_u32 s92, s92, s95
	s_subb_u32 s93, s93, 0
	s_lshl_b32 s94, s94, 10
	s_waitcnt lgkmcnt(0)
	s_barrier
	s_lshl_b32 s95, s94, 2
	s_add_u32 m0, s95, 0x0
	s_nop 0
	global_load_lds_dwordx4 v236, s[90:91]
	global_load_lds_dwordx4 v237, s[90:91] offset:1024
	global_load_lds_dwordx4 v238, s[90:91] offset:2048
	global_load_lds_dwordx4 v239, s[90:91] offset:3072
	s_mul_i32 s95, s94, 4
	s_add_u32 m0, s95, 0x4000
	s_nop 0
	global_load_lds_dwordx4 v240, s[92:93]
	global_load_lds_dwordx4 v241, s[92:93] offset:1024
	global_load_lds_dwordx4 v242, s[92:93] offset:2048
	global_load_lds_dwordx4 v243, s[92:93] offset:3072
	s_add_u32 s90, s90, 0x80
	s_addc_u32 s91, s91, 0
	s_add_u32 s92, s92, 0x80
	s_addc_u32 s93, s93, 0
	s_waitcnt vmcnt(0)
	s_barrier
	s_lshl_b32 s95, s94, 2
	s_add_u32 m0, s95, 0x8000
	s_nop 0
	global_load_lds_dwordx4 v236, s[90:91]
	global_load_lds_dwordx4 v237, s[90:91] offset:1024
	global_load_lds_dwordx4 v238, s[90:91] offset:2048
	global_load_lds_dwordx4 v239, s[90:91] offset:3072
	s_mul_i32 s95, s94, 4
	s_add_u32 m0, s95, 0xc000
	s_nop 0
	global_load_lds_dwordx4 v240, s[92:93]
	global_load_lds_dwordx4 v241, s[92:93] offset:1024
	global_load_lds_dwordx4 v242, s[92:93] offset:2048
	global_load_lds_dwordx4 v243, s[92:93] offset:3072
	s_add_u32 s90, s90, 0x80
	s_addc_u32 s91, s91, 0
	s_add_u32 s92, s92, 0x80
	s_addc_u32 s93, s93, 0
	ds_read_b128 v[110:113], v244 offset:0
	ds_read_b128 v[114:117], v244 offset:2048
	ds_read_b128 v[118:121], v244 offset:4096
	ds_read_b128 v[122:125], v244 offset:6144
	ds_read_b128 v[126:129], v246 offset:0
	ds_read_b128 v[130:133], v246 offset:2048
	ds_read_b128 v[134:137], v246 offset:4096
	ds_read_b128 v[138:141], v246 offset:6144
	s_movk_i32 s95, 0x6
	s_cmp_eq_u32 s95, 0
	s_cbranch_scc1 .Lgemm_x1480
	.p2align	6
